# scan consumer: 8 operand sets, prefetch 3 steps, one lgkm wait per 2 steps, group-3 transposes deferred into next chunk's DPP gaps
# baseline (speedup 1.0000x reference)
.LBB0_56:
	s_and_b64 s[4:5], s[42:43], exec
	s_mov_b32 s4, 0x1caf0000
	s_cselect_b32 s4, s4, 0x14af0000
	s_add_u32 s4, s30, s4
	s_addc_u32 s5, s31, 0
	s_lshl_b32 s6, s37, 1
	v_lshl_add_u32 v0, s64, 4, v58
	s_add_u32 s4, s4, s6
	s_addc_u32 s5, s5, 0
	v_ashrrev_i32_e32 v1, 31, v0
	s_waitcnt lgkmcnt(0)
	s_barrier
	v_lshl_add_u64 v[0:1], v[0:1], 1, s[4:5]
	s_and_b64 s[4:5], s[42:43], exec
	s_movk_i32 s4, 0x4000
	s_mov_b32 s28, 0
	s_cselect_b32 s85, 0, -1
	s_cselect_b32 s84, s4, 0xffffc000
	s_waitcnt vmcnt(0)
	v_mov_b32_e32 v6, 0
	v_mov_b32_e32 v4, v78
	v_mov_b32_e32 v5, v15
	v_mov_b32_e32 v7, 0
	v_mov_b32_e32 v8, 0
	v_mov_b32_e32 v9, 0
	v_lshlrev_b32_e32 v74, 4, v58
	v_add_u32_e32 v74, 0x22000, v74
	s_mov_b64 s[100:101], 0
	v_mov_b32_e32 v10, v59
	v_mov_b32_e32 v11, v74
	ds_read_b128 v[66:69], v11 offset:0
	ds_read_b128 v[20:23], v10 offset:256
	ds_read_b128 v[28:31], v10 offset:768
	ds_read_b128 v[24:27], v10 offset:512
	ds_read_b128 v[36:39], v10 offset:1280
	ds_read_b128 v[44:47], v10 offset:1792
	ds_read_b128 v[40:43], v10 offset:1536
	ds_read_b128 v[88:91], v10 offset:2304
	ds_read_b128 v[96:99], v10 offset:2816
	ds_read_b128 v[92:95], v10 offset:2560
.Lscan_cons_chunk:
	v_cndmask_b32_e64 v2, v4, v5, s[42:43]
	v_add_lshl_u32 v2, v2, s80, 10
	v_mov_b32_e32 v3, v180
	s_add_i32 s28, s28, 0x10000
	v_lshl_add_u64 v[2:3], v[0:1], 0, v[2:3]
	v_add_u32_e32 v5, 64, v5
	v_subrev_u32_e32 v4, 64, v4
	s_waitcnt lgkmcnt(3)
	v_fma_mix_f32 v12, v6, v20, v180 op_sel_hi:[0,1,0]
	v_fma_mix_f32 v12, v7, v20, v12 op_sel:[0,1,0] op_sel_hi:[0,1,0]
	v_fma_mix_f32 v12, v8, v21, v12 op_sel_hi:[0,1,0]
	v_fma_mix_f32 v12, v9, v21, v12 op_sel:[0,1,0] op_sel_hi:[0,1,0]
	s_nop 1
	v_add_f32_dpp v12, v12, v12 row_ror:1 row_mask:0xf bank_mask:0xf bound_ctrl:1
	s_nop 1
	v_add_f32_dpp v12, v12, v12 row_ror:2 row_mask:0xf bank_mask:0xf bound_ctrl:1
	v_pk_fma_f32 v[48:49], v[28:29], v[66:67], v[6:7] op_sel_hi:[1,0,1]
	v_pk_fma_f32 v[50:51], v[30:31], v[66:67], v[8:9] op_sel_hi:[1,0,1]
	v_add_f32_dpp v12, v12, v12 row_ror:4 row_mask:0xf bank_mask:0xf bound_ctrl:1
	v_add_f32_dpp v130, v130, v130 row_ror:8 row_mask:0xf bank_mask:0xc
	v_add_f32_dpp v130, v122, v122 row_ror:8 row_mask:0xf bank_mask:0x3
	v_add_f32_dpp v131, v131, v131 row_ror:8 row_mask:0xf bank_mask:0xc
	v_add_f32_dpp v12, v12, v12 row_ror:8 row_mask:0xf bank_mask:0xf bound_ctrl:1
	v_pk_fma_f32 v[6:7], v[24:25], v[12:13], v[48:49] op_sel_hi:[1,0,1] neg_lo:[1,0,0] neg_hi:[1,0,0]
	v_pk_fma_f32 v[8:9], v[26:27], v[12:13], v[50:51] op_sel_hi:[1,0,1] neg_lo:[1,0,0] neg_hi:[1,0,0]
	ds_read_b128 v[110:113], v10 offset:3328
	ds_read_b128 v[106:109], v10 offset:3072
	ds_read_b128 v[118:121], v10 offset:3840
	ds_read_b128 v[114:117], v10 offset:3584
	v_fma_mix_f32 v12, v6, v36, v180 op_sel_hi:[0,1,0]
	v_fma_mix_f32 v12, v7, v36, v12 op_sel:[0,1,0] op_sel_hi:[0,1,0]
	v_fma_mix_f32 v12, v8, v37, v12 op_sel_hi:[0,1,0]
	v_fma_mix_f32 v12, v9, v37, v12 op_sel:[0,1,0] op_sel_hi:[0,1,0]
	v_fma_mix_f32 v52, v6, v22, v180 op_sel_hi:[0,1,0]
	v_fma_mix_f32 v52, v7, v22, v52 op_sel:[0,1,0] op_sel_hi:[0,1,0]
	v_add_f32_dpp v12, v12, v12 row_ror:1 row_mask:0xf bank_mask:0xf bound_ctrl:1
	v_fma_mix_f32 v52, v8, v23, v52 op_sel_hi:[0,1,0]
	v_fma_mix_f32 v52, v9, v23, v52 op_sel:[0,1,0] op_sel_hi:[0,1,0]
	v_add_f32_dpp v12, v12, v12 row_ror:2 row_mask:0xf bank_mask:0xf bound_ctrl:1
	v_pk_fma_f32 v[48:49], v[44:45], v[66:67], v[6:7] op_sel:[0,1,0]
	v_pk_fma_f32 v[50:51], v[46:47], v[66:67], v[8:9] op_sel:[0,1,0]
	v_add_f32_dpp v12, v12, v12 row_ror:4 row_mask:0xf bank_mask:0xf bound_ctrl:1
	v_add_f32_dpp v131, v123, v123 row_ror:8 row_mask:0xf bank_mask:0x3
	v_add_f32_dpp v132, v132, v132 row_ror:8 row_mask:0xf bank_mask:0xc
	v_add_f32_dpp v132, v124, v124 row_ror:8 row_mask:0xf bank_mask:0x3
	v_add_f32_dpp v12, v12, v12 row_ror:8 row_mask:0xf bank_mask:0xf bound_ctrl:1
	v_pk_fma_f32 v[6:7], v[40:41], v[12:13], v[48:49] op_sel_hi:[1,0,1] neg_lo:[1,0,0] neg_hi:[1,0,0]
	v_pk_fma_f32 v[8:9], v[42:43], v[12:13], v[50:51] op_sel_hi:[1,0,1] neg_lo:[1,0,0] neg_hi:[1,0,0]
	ds_read_b128 v[142:145], v10 offset:4352
	ds_read_b128 v[150:153], v10 offset:4864
	ds_read_b128 v[146:149], v10 offset:4608
	ds_read_b128 v[70:73], v11 offset:256
	s_waitcnt lgkmcnt(4)
	v_fma_mix_f32 v12, v6, v88, v180 op_sel_hi:[0,1,0]
	v_fma_mix_f32 v12, v7, v88, v12 op_sel:[0,1,0] op_sel_hi:[0,1,0]
	v_fma_mix_f32 v12, v8, v89, v12 op_sel_hi:[0,1,0]
	v_fma_mix_f32 v12, v9, v89, v12 op_sel:[0,1,0] op_sel_hi:[0,1,0]
	v_fma_mix_f32 v53, v6, v38, v180 op_sel_hi:[0,1,0]
	v_fma_mix_f32 v53, v7, v38, v53 op_sel:[0,1,0] op_sel_hi:[0,1,0]
	v_add_f32_dpp v12, v12, v12 row_ror:1 row_mask:0xf bank_mask:0xf bound_ctrl:1
	v_fma_mix_f32 v53, v8, v39, v53 op_sel_hi:[0,1,0]
	v_fma_mix_f32 v53, v9, v39, v53 op_sel:[0,1,0] op_sel_hi:[0,1,0]
	v_add_f32_dpp v12, v12, v12 row_ror:2 row_mask:0xf bank_mask:0xf bound_ctrl:1
	v_pk_fma_f32 v[48:49], v[96:97], v[68:69], v[6:7] op_sel_hi:[1,0,1]
	v_pk_fma_f32 v[50:51], v[98:99], v[68:69], v[8:9] op_sel_hi:[1,0,1]
	v_add_f32_dpp v12, v12, v12 row_ror:4 row_mask:0xf bank_mask:0xf bound_ctrl:1
	v_add_f32_dpp v133, v133, v133 row_ror:8 row_mask:0xf bank_mask:0xc
	v_add_f32_dpp v133, v125, v125 row_ror:8 row_mask:0xf bank_mask:0x3
	v_add_f32_dpp v134, v134, v134 row_ror:8 row_mask:0xf bank_mask:0xc
	v_add_f32_dpp v12, v12, v12 row_ror:8 row_mask:0xf bank_mask:0xf bound_ctrl:1
	v_pk_fma_f32 v[6:7], v[92:93], v[12:13], v[48:49] op_sel_hi:[1,0,1] neg_lo:[1,0,0] neg_hi:[1,0,0]
	v_pk_fma_f32 v[8:9], v[94:95], v[12:13], v[50:51] op_sel_hi:[1,0,1] neg_lo:[1,0,0] neg_hi:[1,0,0]
	ds_read_b128 v[158:161], v10 offset:5376
	ds_read_b128 v[166:169], v10 offset:5888
	ds_read_b128 v[162:165], v10 offset:5632
	v_fma_mix_f32 v12, v6, v110, v180 op_sel_hi:[0,1,0]
	v_fma_mix_f32 v12, v7, v110, v12 op_sel:[0,1,0] op_sel_hi:[0,1,0]
	v_fma_mix_f32 v12, v8, v111, v12 op_sel_hi:[0,1,0]
	v_fma_mix_f32 v12, v9, v111, v12 op_sel:[0,1,0] op_sel_hi:[0,1,0]
	v_fma_mix_f32 v54, v6, v90, v180 op_sel_hi:[0,1,0]
	v_fma_mix_f32 v54, v7, v90, v54 op_sel:[0,1,0] op_sel_hi:[0,1,0]
	v_add_f32_dpp v12, v12, v12 row_ror:1 row_mask:0xf bank_mask:0xf bound_ctrl:1
	v_fma_mix_f32 v54, v8, v91, v54 op_sel_hi:[0,1,0]
	v_fma_mix_f32 v54, v9, v91, v54 op_sel:[0,1,0] op_sel_hi:[0,1,0]
	v_add_f32_dpp v12, v12, v12 row_ror:2 row_mask:0xf bank_mask:0xf bound_ctrl:1
	v_pk_fma_f32 v[48:49], v[118:119], v[68:69], v[6:7] op_sel:[0,1,0]
	v_pk_fma_f32 v[50:51], v[120:121], v[68:69], v[8:9] op_sel:[0,1,0]
	v_add_f32_dpp v12, v12, v12 row_ror:4 row_mask:0xf bank_mask:0xf bound_ctrl:1
	v_add_f32_dpp v134, v126, v126 row_ror:8 row_mask:0xf bank_mask:0x3
	v_add_f32_dpp v135, v135, v135 row_ror:8 row_mask:0xf bank_mask:0xc
	v_add_f32_dpp v135, v127, v127 row_ror:8 row_mask:0xf bank_mask:0x3
	v_add_f32_dpp v12, v12, v12 row_ror:8 row_mask:0xf bank_mask:0xf bound_ctrl:1
	v_pk_fma_f32 v[6:7], v[114:115], v[12:13], v[48:49] op_sel_hi:[1,0,1] neg_lo:[1,0,0] neg_hi:[1,0,0]
	v_pk_fma_f32 v[8:9], v[116:117], v[12:13], v[50:51] op_sel_hi:[1,0,1] neg_lo:[1,0,0] neg_hi:[1,0,0]
	v_pk_mul_f32 v[6:7], v[6:7], v[106:107]
	v_pk_mul_f32 v[8:9], v[8:9], v[108:109]
	ds_read_b128 v[188:191], v10 offset:6400
	ds_read_b128 v[196:199], v10 offset:6912
	ds_read_b128 v[192:195], v10 offset:6656
	s_waitcnt lgkmcnt(3)
	v_fma_mix_f32 v12, v6, v142, v180 op_sel_hi:[0,1,0]
	v_fma_mix_f32 v12, v7, v142, v12 op_sel:[0,1,0] op_sel_hi:[0,1,0]
	v_fma_mix_f32 v12, v8, v143, v12 op_sel_hi:[0,1,0]
	v_fma_mix_f32 v12, v9, v143, v12 op_sel:[0,1,0] op_sel_hi:[0,1,0]
	v_fma_mix_f32 v55, v6, v112, v180 op_sel_hi:[0,1,0]
	v_fma_mix_f32 v55, v7, v112, v55 op_sel:[0,1,0] op_sel_hi:[0,1,0]
	v_add_f32_dpp v12, v12, v12 row_ror:1 row_mask:0xf bank_mask:0xf bound_ctrl:1
	v_fma_mix_f32 v55, v8, v113, v55 op_sel_hi:[0,1,0]
	v_fma_mix_f32 v55, v9, v113, v55 op_sel:[0,1,0] op_sel_hi:[0,1,0]
	v_add_f32_dpp v12, v12, v12 row_ror:2 row_mask:0xf bank_mask:0xf bound_ctrl:1
	v_pk_fma_f32 v[48:49], v[150:151], v[70:71], v[6:7] op_sel_hi:[1,0,1]
	v_pk_fma_f32 v[50:51], v[152:153], v[70:71], v[8:9] op_sel_hi:[1,0,1]
	v_add_f32_dpp v12, v12, v12 row_ror:4 row_mask:0xf bank_mask:0xf bound_ctrl:1
	v_add_f32_dpp v136, v136, v136 row_ror:8 row_mask:0xf bank_mask:0xc
	v_add_f32_dpp v136, v128, v128 row_ror:8 row_mask:0xf bank_mask:0x3
	v_add_f32_dpp v12, v12, v12 row_ror:8 row_mask:0xf bank_mask:0xf bound_ctrl:1
	v_pk_fma_f32 v[6:7], v[146:147], v[12:13], v[48:49] op_sel_hi:[1,0,1] neg_lo:[1,0,0] neg_hi:[1,0,0]
	v_pk_fma_f32 v[8:9], v[148:149], v[12:13], v[50:51] op_sel_hi:[1,0,1] neg_lo:[1,0,0] neg_hi:[1,0,0]
	ds_read_b128 v[204:207], v10 offset:7424
	ds_read_b128 v[200:203], v10 offset:7168
	ds_read_b128 v[212:215], v10 offset:7936
	ds_read_b128 v[208:211], v10 offset:7680
	v_fma_mix_f32 v12, v6, v158, v180 op_sel_hi:[0,1,0]
	v_fma_mix_f32 v12, v7, v158, v12 op_sel:[0,1,0] op_sel_hi:[0,1,0]
	v_fma_mix_f32 v12, v8, v159, v12 op_sel_hi:[0,1,0]
	v_fma_mix_f32 v12, v9, v159, v12 op_sel:[0,1,0] op_sel_hi:[0,1,0]
	v_fma_mix_f32 v56, v6, v144, v180 op_sel_hi:[0,1,0]
	v_fma_mix_f32 v56, v7, v144, v56 op_sel:[0,1,0] op_sel_hi:[0,1,0]
	v_add_f32_dpp v12, v12, v12 row_ror:1 row_mask:0xf bank_mask:0xf bound_ctrl:1
	v_fma_mix_f32 v56, v8, v145, v56 op_sel_hi:[0,1,0]
	v_fma_mix_f32 v56, v9, v145, v56 op_sel:[0,1,0] op_sel_hi:[0,1,0]
	v_add_f32_dpp v12, v12, v12 row_ror:2 row_mask:0xf bank_mask:0xf bound_ctrl:1
	v_pk_fma_f32 v[48:49], v[166:167], v[70:71], v[6:7] op_sel:[0,1,0]
	v_pk_fma_f32 v[50:51], v[168:169], v[70:71], v[8:9] op_sel:[0,1,0]
	v_add_f32_dpp v12, v12, v12 row_ror:4 row_mask:0xf bank_mask:0xf bound_ctrl:1
	v_add_f32_dpp v137, v137, v137 row_ror:8 row_mask:0xf bank_mask:0xc
	v_add_f32_dpp v137, v129, v129 row_ror:8 row_mask:0xf bank_mask:0x3
	v_add_f32_dpp v12, v12, v12 row_ror:8 row_mask:0xf bank_mask:0xf bound_ctrl:1
	v_pk_fma_f32 v[6:7], v[162:163], v[12:13], v[48:49] op_sel_hi:[1,0,1] neg_lo:[1,0,0] neg_hi:[1,0,0]
	v_pk_fma_f32 v[8:9], v[164:165], v[12:13], v[50:51] op_sel_hi:[1,0,1] neg_lo:[1,0,0] neg_hi:[1,0,0]
	ds_read_b128 v[20:23], v10 offset:8448
	ds_read_b128 v[28:31], v10 offset:8960
	ds_read_b128 v[24:27], v10 offset:8704
	ds_read_b128 v[66:69], v11 offset:512
	s_waitcnt lgkmcnt(4)
	v_fma_mix_f32 v12, v6, v188, v180 op_sel_hi:[0,1,0]
	v_fma_mix_f32 v12, v7, v188, v12 op_sel:[0,1,0] op_sel_hi:[0,1,0]
	v_fma_mix_f32 v12, v8, v189, v12 op_sel_hi:[0,1,0]
	v_fma_mix_f32 v12, v9, v189, v12 op_sel:[0,1,0] op_sel_hi:[0,1,0]
	v_fma_mix_f32 v57, v6, v160, v180 op_sel_hi:[0,1,0]
	v_fma_mix_f32 v57, v7, v160, v57 op_sel:[0,1,0] op_sel_hi:[0,1,0]
	v_add_f32_dpp v12, v12, v12 row_ror:1 row_mask:0xf bank_mask:0xf bound_ctrl:1
	v_fma_mix_f32 v57, v8, v161, v57 op_sel_hi:[0,1,0]
	v_fma_mix_f32 v57, v9, v161, v57 op_sel:[0,1,0] op_sel_hi:[0,1,0]
	v_add_f32_dpp v12, v12, v12 row_ror:2 row_mask:0xf bank_mask:0xf bound_ctrl:1
	v_pk_fma_f32 v[48:49], v[196:197], v[72:73], v[6:7] op_sel_hi:[1,0,1]
	v_pk_fma_f32 v[50:51], v[198:199], v[72:73], v[8:9] op_sel_hi:[1,0,1]
	v_add_f32_dpp v12, v12, v12 row_ror:4 row_mask:0xf bank_mask:0xf bound_ctrl:1
	v_add_f32_dpp v134, v134, v134 row_ror:4 row_mask:0xf bank_mask:0xa
	v_add_f32_dpp v134, v130, v130 row_ror:12 row_mask:0xf bank_mask:0x5
	v_add_f32_dpp v135, v135, v135 row_ror:4 row_mask:0xf bank_mask:0xa
	v_add_f32_dpp v12, v12, v12 row_ror:8 row_mask:0xf bank_mask:0xf bound_ctrl:1
	v_pk_fma_f32 v[6:7], v[192:193], v[12:13], v[48:49] op_sel_hi:[1,0,1] neg_lo:[1,0,0] neg_hi:[1,0,0]
	v_pk_fma_f32 v[8:9], v[194:195], v[12:13], v[50:51] op_sel_hi:[1,0,1] neg_lo:[1,0,0] neg_hi:[1,0,0]
	ds_read_b128 v[36:39], v10 offset:9472
	ds_read_b128 v[44:47], v10 offset:9984
	ds_read_b128 v[40:43], v10 offset:9728
	v_fma_mix_f32 v12, v6, v204, v180 op_sel_hi:[0,1,0]
	v_fma_mix_f32 v12, v7, v204, v12 op_sel:[0,1,0] op_sel_hi:[0,1,0]
	v_fma_mix_f32 v12, v8, v205, v12 op_sel_hi:[0,1,0]
	v_fma_mix_f32 v12, v9, v205, v12 op_sel:[0,1,0] op_sel_hi:[0,1,0]
	v_fma_mix_f32 v81, v6, v190, v180 op_sel_hi:[0,1,0]
	v_fma_mix_f32 v81, v7, v190, v81 op_sel:[0,1,0] op_sel_hi:[0,1,0]
	v_add_f32_dpp v12, v12, v12 row_ror:1 row_mask:0xf bank_mask:0xf bound_ctrl:1
	v_fma_mix_f32 v81, v8, v191, v81 op_sel_hi:[0,1,0]
	v_fma_mix_f32 v81, v9, v191, v81 op_sel:[0,1,0] op_sel_hi:[0,1,0]
	v_add_f32_dpp v12, v12, v12 row_ror:2 row_mask:0xf bank_mask:0xf bound_ctrl:1
	v_pk_fma_f32 v[48:49], v[212:213], v[72:73], v[6:7] op_sel:[0,1,0]
	v_pk_fma_f32 v[50:51], v[214:215], v[72:73], v[8:9] op_sel:[0,1,0]
	v_add_f32_dpp v12, v12, v12 row_ror:4 row_mask:0xf bank_mask:0xf bound_ctrl:1
	v_add_f32_dpp v135, v131, v131 row_ror:12 row_mask:0xf bank_mask:0x5
	v_add_f32_dpp v136, v136, v136 row_ror:4 row_mask:0xf bank_mask:0xa
	v_add_f32_dpp v136, v132, v132 row_ror:12 row_mask:0xf bank_mask:0x5
	v_add_f32_dpp v12, v12, v12 row_ror:8 row_mask:0xf bank_mask:0xf bound_ctrl:1
	v_pk_fma_f32 v[6:7], v[208:209], v[12:13], v[48:49] op_sel_hi:[1,0,1] neg_lo:[1,0,0] neg_hi:[1,0,0]
	v_pk_fma_f32 v[8:9], v[210:211], v[12:13], v[50:51] op_sel_hi:[1,0,1] neg_lo:[1,0,0] neg_hi:[1,0,0]
	v_pk_mul_f32 v[6:7], v[6:7], v[200:201]
	v_pk_mul_f32 v[8:9], v[8:9], v[202:203]
	ds_read_b128 v[88:91], v10 offset:10496
	ds_read_b128 v[96:99], v10 offset:11008
	ds_read_b128 v[92:95], v10 offset:10752
	s_waitcnt lgkmcnt(3)
	v_fma_mix_f32 v12, v6, v20, v180 op_sel_hi:[0,1,0]
	v_fma_mix_f32 v12, v7, v20, v12 op_sel:[0,1,0] op_sel_hi:[0,1,0]
	v_fma_mix_f32 v12, v8, v21, v12 op_sel_hi:[0,1,0]
	v_fma_mix_f32 v12, v9, v21, v12 op_sel:[0,1,0] op_sel_hi:[0,1,0]
	v_fma_mix_f32 v82, v6, v206, v180 op_sel_hi:[0,1,0]
	v_fma_mix_f32 v82, v7, v206, v82 op_sel:[0,1,0] op_sel_hi:[0,1,0]
	v_add_f32_dpp v12, v12, v12 row_ror:1 row_mask:0xf bank_mask:0xf bound_ctrl:1
	v_fma_mix_f32 v82, v8, v207, v82 op_sel_hi:[0,1,0]
	v_fma_mix_f32 v82, v9, v207, v82 op_sel:[0,1,0] op_sel_hi:[0,1,0]
	v_add_f32_dpp v12, v12, v12 row_ror:2 row_mask:0xf bank_mask:0xf bound_ctrl:1
	v_pk_fma_f32 v[48:49], v[28:29], v[66:67], v[6:7] op_sel_hi:[1,0,1]
	v_pk_fma_f32 v[50:51], v[30:31], v[66:67], v[8:9] op_sel_hi:[1,0,1]
	v_add_f32_dpp v12, v12, v12 row_ror:4 row_mask:0xf bank_mask:0xf bound_ctrl:1
	v_add_f32_dpp v137, v137, v137 row_ror:4 row_mask:0xf bank_mask:0xa
	v_add_f32_dpp v137, v133, v133 row_ror:12 row_mask:0xf bank_mask:0x5
	v_add_f32_dpp v12, v12, v12 row_ror:8 row_mask:0xf bank_mask:0xf bound_ctrl:1
	v_pk_fma_f32 v[6:7], v[24:25], v[12:13], v[48:49] op_sel_hi:[1,0,1] neg_lo:[1,0,0] neg_hi:[1,0,0]
	v_pk_fma_f32 v[8:9], v[26:27], v[12:13], v[50:51] op_sel_hi:[1,0,1] neg_lo:[1,0,0] neg_hi:[1,0,0]
	ds_read_b128 v[110:113], v10 offset:11520
	ds_read_b128 v[106:109], v10 offset:11264
	ds_read_b128 v[118:121], v10 offset:12032
	ds_read_b128 v[114:117], v10 offset:11776
	v_fma_mix_f32 v12, v6, v36, v180 op_sel_hi:[0,1,0]
	v_fma_mix_f32 v12, v7, v36, v12 op_sel:[0,1,0] op_sel_hi:[0,1,0]
	v_fma_mix_f32 v12, v8, v37, v12 op_sel_hi:[0,1,0]
	v_fma_mix_f32 v12, v9, v37, v12 op_sel:[0,1,0] op_sel_hi:[0,1,0]
	v_fma_mix_f32 v83, v6, v22, v180 op_sel_hi:[0,1,0]
	v_fma_mix_f32 v83, v7, v22, v83 op_sel:[0,1,0] op_sel_hi:[0,1,0]
	v_add_f32_dpp v12, v12, v12 row_ror:1 row_mask:0xf bank_mask:0xf bound_ctrl:1
	v_fma_mix_f32 v83, v8, v23, v83 op_sel_hi:[0,1,0]
	v_fma_mix_f32 v83, v9, v23, v83 op_sel:[0,1,0] op_sel_hi:[0,1,0]
	v_add_f32_dpp v12, v12, v12 row_ror:2 row_mask:0xf bank_mask:0xf bound_ctrl:1
	v_pk_fma_f32 v[48:49], v[44:45], v[66:67], v[6:7] op_sel:[0,1,0]
	v_pk_fma_f32 v[50:51], v[46:47], v[66:67], v[8:9] op_sel:[0,1,0]
	v_add_f32_dpp v12, v12, v12 row_ror:4 row_mask:0xf bank_mask:0xf bound_ctrl:1
	v_cndmask_b32_e64 v62, v136, v134, s[38:39]
	v_cndmask_b32_e64 v63, v134, v136, s[38:39]
	v_add_f32_dpp v12, v12, v12 row_ror:8 row_mask:0xf bank_mask:0xf bound_ctrl:1
	v_pk_fma_f32 v[6:7], v[40:41], v[12:13], v[48:49] op_sel_hi:[1,0,1] neg_lo:[1,0,0] neg_hi:[1,0,0]
	v_pk_fma_f32 v[8:9], v[42:43], v[12:13], v[50:51] op_sel_hi:[1,0,1] neg_lo:[1,0,0] neg_hi:[1,0,0]
	ds_read_b128 v[142:145], v10 offset:12544
	ds_read_b128 v[150:153], v10 offset:13056
	ds_read_b128 v[146:149], v10 offset:12800
	ds_read_b128 v[70:73], v11 offset:768
	s_waitcnt lgkmcnt(4)
	v_fma_mix_f32 v12, v6, v88, v180 op_sel_hi:[0,1,0]
	v_fma_mix_f32 v12, v7, v88, v12 op_sel:[0,1,0] op_sel_hi:[0,1,0]
	v_fma_mix_f32 v12, v8, v89, v12 op_sel_hi:[0,1,0]
	v_fma_mix_f32 v12, v9, v89, v12 op_sel:[0,1,0] op_sel_hi:[0,1,0]
	v_fma_mix_f32 v100, v6, v38, v180 op_sel_hi:[0,1,0]
	v_fma_mix_f32 v100, v7, v38, v100 op_sel:[0,1,0] op_sel_hi:[0,1,0]
	v_add_f32_dpp v12, v12, v12 row_ror:1 row_mask:0xf bank_mask:0xf bound_ctrl:1
	v_fma_mix_f32 v100, v8, v39, v100 op_sel_hi:[0,1,0]
	v_fma_mix_f32 v100, v9, v39, v100 op_sel:[0,1,0] op_sel_hi:[0,1,0]
	v_add_f32_dpp v12, v12, v12 row_ror:2 row_mask:0xf bank_mask:0xf bound_ctrl:1
	v_pk_fma_f32 v[48:49], v[96:97], v[68:69], v[6:7] op_sel_hi:[1,0,1]
	v_pk_fma_f32 v[50:51], v[98:99], v[68:69], v[8:9] op_sel_hi:[1,0,1]
	v_add_f32_dpp v12, v12, v12 row_ror:4 row_mask:0xf bank_mask:0xf bound_ctrl:1
	v_cndmask_b32_e64 v64, v137, v135, s[38:39]
	v_cndmask_b32_e64 v65, v135, v137, s[38:39]
	v_add_f32_dpp v12, v12, v12 row_ror:8 row_mask:0xf bank_mask:0xf bound_ctrl:1
	v_pk_fma_f32 v[6:7], v[92:93], v[12:13], v[48:49] op_sel_hi:[1,0,1] neg_lo:[1,0,0] neg_hi:[1,0,0]
	v_pk_fma_f32 v[8:9], v[94:95], v[12:13], v[50:51] op_sel_hi:[1,0,1] neg_lo:[1,0,0] neg_hi:[1,0,0]
	ds_read_b128 v[158:161], v10 offset:13568
	ds_read_b128 v[166:169], v10 offset:14080
	ds_read_b128 v[162:165], v10 offset:13824
	v_fma_mix_f32 v12, v6, v110, v180 op_sel_hi:[0,1,0]
	v_fma_mix_f32 v12, v7, v110, v12 op_sel:[0,1,0] op_sel_hi:[0,1,0]
	v_fma_mix_f32 v12, v8, v111, v12 op_sel_hi:[0,1,0]
	v_fma_mix_f32 v12, v9, v111, v12 op_sel:[0,1,0] op_sel_hi:[0,1,0]
	v_fma_mix_f32 v101, v6, v90, v180 op_sel_hi:[0,1,0]
	v_fma_mix_f32 v101, v7, v90, v101 op_sel:[0,1,0] op_sel_hi:[0,1,0]
	v_add_f32_dpp v12, v12, v12 row_ror:1 row_mask:0xf bank_mask:0xf bound_ctrl:1
	v_fma_mix_f32 v101, v8, v91, v101 op_sel_hi:[0,1,0]
	v_fma_mix_f32 v101, v9, v91, v101 op_sel:[0,1,0] op_sel_hi:[0,1,0]
	v_add_f32_dpp v12, v12, v12 row_ror:2 row_mask:0xf bank_mask:0xf bound_ctrl:1
	v_pk_fma_f32 v[48:49], v[118:119], v[68:69], v[6:7] op_sel:[0,1,0]
	v_pk_fma_f32 v[50:51], v[120:121], v[68:69], v[8:9] op_sel:[0,1,0]
	v_add_f32_dpp v12, v12, v12 row_ror:4 row_mask:0xf bank_mask:0xf bound_ctrl:1
	v_add_f32_dpp v62, v63, v62 quad_perm:[2,3,0,1] row_mask:0xf bank_mask:0xf bound_ctrl:1
	v_add_f32_dpp v63, v65, v64 quad_perm:[2,3,0,1] row_mask:0xf bank_mask:0xf bound_ctrl:1
	v_add_f32_dpp v12, v12, v12 row_ror:8 row_mask:0xf bank_mask:0xf bound_ctrl:1
	v_pk_fma_f32 v[6:7], v[114:115], v[12:13], v[48:49] op_sel_hi:[1,0,1] neg_lo:[1,0,0] neg_hi:[1,0,0]
	v_pk_fma_f32 v[8:9], v[116:117], v[12:13], v[50:51] op_sel_hi:[1,0,1] neg_lo:[1,0,0] neg_hi:[1,0,0]
	v_pk_mul_f32 v[6:7], v[6:7], v[106:107]
	v_pk_mul_f32 v[8:9], v[8:9], v[108:109]
	ds_read_b128 v[188:191], v10 offset:14592
	ds_read_b128 v[196:199], v10 offset:15104
	ds_read_b128 v[192:195], v10 offset:14848
	s_waitcnt lgkmcnt(3)
	v_fma_mix_f32 v12, v6, v142, v180 op_sel_hi:[0,1,0]
	v_fma_mix_f32 v12, v7, v142, v12 op_sel:[0,1,0] op_sel_hi:[0,1,0]
	v_fma_mix_f32 v12, v8, v143, v12 op_sel_hi:[0,1,0]
	v_fma_mix_f32 v12, v9, v143, v12 op_sel:[0,1,0] op_sel_hi:[0,1,0]
	v_fma_mix_f32 v102, v6, v112, v180 op_sel_hi:[0,1,0]
	v_fma_mix_f32 v102, v7, v112, v102 op_sel:[0,1,0] op_sel_hi:[0,1,0]
	v_add_f32_dpp v12, v12, v12 row_ror:1 row_mask:0xf bank_mask:0xf bound_ctrl:1
	v_fma_mix_f32 v102, v8, v113, v102 op_sel_hi:[0,1,0]
	v_fma_mix_f32 v102, v9, v113, v102 op_sel:[0,1,0] op_sel_hi:[0,1,0]
	v_add_f32_dpp v12, v12, v12 row_ror:2 row_mask:0xf bank_mask:0xf bound_ctrl:1
	v_pk_fma_f32 v[48:49], v[150:151], v[70:71], v[6:7] op_sel_hi:[1,0,1]
	v_pk_fma_f32 v[50:51], v[152:153], v[70:71], v[8:9] op_sel_hi:[1,0,1]
	v_add_f32_dpp v12, v12, v12 row_ror:4 row_mask:0xf bank_mask:0xf bound_ctrl:1
	v_cndmask_b32_e64 v65, v63, v62, s[40:41]
	v_cndmask_b32_e64 v62, v62, v63, s[40:41]
	v_add_f32_dpp v12, v12, v12 row_ror:8 row_mask:0xf bank_mask:0xf bound_ctrl:1
	v_pk_fma_f32 v[6:7], v[146:147], v[12:13], v[48:49] op_sel_hi:[1,0,1] neg_lo:[1,0,0] neg_hi:[1,0,0]
	v_pk_fma_f32 v[8:9], v[148:149], v[12:13], v[50:51] op_sel_hi:[1,0,1] neg_lo:[1,0,0] neg_hi:[1,0,0]
	ds_read_b128 v[204:207], v10 offset:15616
	ds_read_b128 v[200:203], v10 offset:15360
	ds_read_b128 v[212:215], v10 offset:16128
	ds_read_b128 v[208:211], v10 offset:15872
	v_fma_mix_f32 v12, v6, v158, v180 op_sel_hi:[0,1,0]
	v_fma_mix_f32 v12, v7, v158, v12 op_sel:[0,1,0] op_sel_hi:[0,1,0]
	v_fma_mix_f32 v12, v8, v159, v12 op_sel_hi:[0,1,0]
	v_fma_mix_f32 v12, v9, v159, v12 op_sel:[0,1,0] op_sel_hi:[0,1,0]
	v_fma_mix_f32 v103, v6, v144, v180 op_sel_hi:[0,1,0]
	v_fma_mix_f32 v103, v7, v144, v103 op_sel:[0,1,0] op_sel_hi:[0,1,0]
	v_add_f32_dpp v12, v12, v12 row_ror:1 row_mask:0xf bank_mask:0xf bound_ctrl:1
	v_fma_mix_f32 v103, v8, v145, v103 op_sel_hi:[0,1,0]
	v_fma_mix_f32 v103, v9, v145, v103 op_sel:[0,1,0] op_sel_hi:[0,1,0]
	v_add_f32_dpp v12, v12, v12 row_ror:2 row_mask:0xf bank_mask:0xf bound_ctrl:1
	v_pk_fma_f32 v[48:49], v[166:167], v[70:71], v[6:7] op_sel:[0,1,0]
	v_pk_fma_f32 v[50:51], v[168:169], v[70:71], v[8:9] op_sel:[0,1,0]
	v_add_f32_dpp v12, v12, v12 row_ror:4 row_mask:0xf bank_mask:0xf bound_ctrl:1
	v_add_f32_dpp v62, v62, v65 quad_perm:[1,0,3,2] row_mask:0xf bank_mask:0xf bound_ctrl:1
	v_cvt_pk_bf16_f32 v62, v62, v62
	v_add_f32_dpp v12, v12, v12 row_ror:8 row_mask:0xf bank_mask:0xf bound_ctrl:1
	v_pk_fma_f32 v[6:7], v[162:163], v[12:13], v[48:49] op_sel_hi:[1,0,1] neg_lo:[1,0,0] neg_hi:[1,0,0]
	v_pk_fma_f32 v[8:9], v[164:165], v[12:13], v[50:51] op_sel_hi:[1,0,1] neg_lo:[1,0,0] neg_hi:[1,0,0]
	ds_read_b128 v[20:23], v10 offset:16640
	ds_read_b128 v[28:31], v10 offset:17152
	ds_read_b128 v[24:27], v10 offset:16896
	ds_read_b128 v[66:69], v11 offset:1024
	s_waitcnt lgkmcnt(4)
	v_fma_mix_f32 v12, v6, v188, v180 op_sel_hi:[0,1,0]
	v_fma_mix_f32 v12, v7, v188, v12 op_sel:[0,1,0] op_sel_hi:[0,1,0]
	v_fma_mix_f32 v12, v8, v189, v12 op_sel_hi:[0,1,0]
	v_fma_mix_f32 v12, v9, v189, v12 op_sel:[0,1,0] op_sel_hi:[0,1,0]
	v_fma_mix_f32 v104, v6, v160, v180 op_sel_hi:[0,1,0]
	v_fma_mix_f32 v104, v7, v160, v104 op_sel:[0,1,0] op_sel_hi:[0,1,0]
	v_add_f32_dpp v12, v12, v12 row_ror:1 row_mask:0xf bank_mask:0xf bound_ctrl:1
	v_fma_mix_f32 v104, v8, v161, v104 op_sel_hi:[0,1,0]
	v_fma_mix_f32 v104, v9, v161, v104 op_sel:[0,1,0] op_sel_hi:[0,1,0]
	v_add_f32_dpp v12, v12, v12 row_ror:2 row_mask:0xf bank_mask:0xf bound_ctrl:1
	v_pk_fma_f32 v[48:49], v[196:197], v[72:73], v[6:7] op_sel_hi:[1,0,1]
	v_pk_fma_f32 v[50:51], v[198:199], v[72:73], v[8:9] op_sel_hi:[1,0,1]
	v_add_f32_dpp v12, v12, v12 row_ror:4 row_mask:0xf bank_mask:0xf bound_ctrl:1
	s_mov_b64 exec, s[100:101]
	global_store_short v[170:171], v62, off
	s_mov_b64 exec, -1
	v_add_f32_dpp v12, v12, v12 row_ror:8 row_mask:0xf bank_mask:0xf bound_ctrl:1
	v_pk_fma_f32 v[6:7], v[192:193], v[12:13], v[48:49] op_sel_hi:[1,0,1] neg_lo:[1,0,0] neg_hi:[1,0,0]
	v_pk_fma_f32 v[8:9], v[194:195], v[12:13], v[50:51] op_sel_hi:[1,0,1] neg_lo:[1,0,0] neg_hi:[1,0,0]
	ds_read_b128 v[36:39], v10 offset:17664
	ds_read_b128 v[44:47], v10 offset:18176
	ds_read_b128 v[40:43], v10 offset:17920
	v_fma_mix_f32 v12, v6, v204, v180 op_sel_hi:[0,1,0]
	v_fma_mix_f32 v12, v7, v204, v12 op_sel:[0,1,0] op_sel_hi:[0,1,0]
	v_fma_mix_f32 v12, v8, v205, v12 op_sel_hi:[0,1,0]
	v_fma_mix_f32 v12, v9, v205, v12 op_sel:[0,1,0] op_sel_hi:[0,1,0]
	v_fma_mix_f32 v105, v6, v190, v180 op_sel_hi:[0,1,0]
	v_fma_mix_f32 v105, v7, v190, v105 op_sel:[0,1,0] op_sel_hi:[0,1,0]
	v_add_f32_dpp v12, v12, v12 row_ror:1 row_mask:0xf bank_mask:0xf bound_ctrl:1
	v_fma_mix_f32 v105, v8, v191, v105 op_sel_hi:[0,1,0]
	v_fma_mix_f32 v105, v9, v191, v105 op_sel:[0,1,0] op_sel_hi:[0,1,0]
	v_add_f32_dpp v12, v12, v12 row_ror:2 row_mask:0xf bank_mask:0xf bound_ctrl:1
	v_pk_fma_f32 v[48:49], v[212:213], v[72:73], v[6:7] op_sel:[0,1,0]
	v_pk_fma_f32 v[50:51], v[214:215], v[72:73], v[8:9] op_sel:[0,1,0]
	v_add_f32_dpp v12, v12, v12 row_ror:4 row_mask:0xf bank_mask:0xf bound_ctrl:1
	s_nop 1
	v_add_f32_dpp v12, v12, v12 row_ror:8 row_mask:0xf bank_mask:0xf bound_ctrl:1
	v_pk_fma_f32 v[6:7], v[208:209], v[12:13], v[48:49] op_sel_hi:[1,0,1] neg_lo:[1,0,0] neg_hi:[1,0,0]
	v_pk_fma_f32 v[8:9], v[210:211], v[12:13], v[50:51] op_sel_hi:[1,0,1] neg_lo:[1,0,0] neg_hi:[1,0,0]
	v_pk_mul_f32 v[6:7], v[6:7], v[200:201]
	v_pk_mul_f32 v[8:9], v[8:9], v[202:203]
	ds_read_b128 v[88:91], v10 offset:18688
	ds_read_b128 v[96:99], v10 offset:19200
	ds_read_b128 v[92:95], v10 offset:18944
	s_waitcnt lgkmcnt(3)
	v_fma_mix_f32 v12, v6, v20, v180 op_sel_hi:[0,1,0]
	v_fma_mix_f32 v12, v7, v20, v12 op_sel:[0,1,0] op_sel_hi:[0,1,0]
	v_fma_mix_f32 v12, v8, v21, v12 op_sel_hi:[0,1,0]
	v_fma_mix_f32 v12, v9, v21, v12 op_sel:[0,1,0] op_sel_hi:[0,1,0]
	v_fma_mix_f32 v61, v6, v206, v180 op_sel_hi:[0,1,0]
	v_fma_mix_f32 v61, v7, v206, v61 op_sel:[0,1,0] op_sel_hi:[0,1,0]
	v_add_f32_dpp v12, v12, v12 row_ror:1 row_mask:0xf bank_mask:0xf bound_ctrl:1
	v_fma_mix_f32 v61, v8, v207, v61 op_sel_hi:[0,1,0]
	v_fma_mix_f32 v61, v9, v207, v61 op_sel:[0,1,0] op_sel_hi:[0,1,0]
	v_add_f32_dpp v12, v12, v12 row_ror:2 row_mask:0xf bank_mask:0xf bound_ctrl:1
	v_pk_fma_f32 v[48:49], v[28:29], v[66:67], v[6:7] op_sel_hi:[1,0,1]
	v_pk_fma_f32 v[50:51], v[30:31], v[66:67], v[8:9] op_sel_hi:[1,0,1]
	v_add_f32_dpp v12, v12, v12 row_ror:4 row_mask:0xf bank_mask:0xf bound_ctrl:1
	s_nop 1
	v_add_f32_dpp v12, v12, v12 row_ror:8 row_mask:0xf bank_mask:0xf bound_ctrl:1
	v_pk_fma_f32 v[6:7], v[24:25], v[12:13], v[48:49] op_sel_hi:[1,0,1] neg_lo:[1,0,0] neg_hi:[1,0,0]
	v_pk_fma_f32 v[8:9], v[26:27], v[12:13], v[50:51] op_sel_hi:[1,0,1] neg_lo:[1,0,0] neg_hi:[1,0,0]
	ds_read_b128 v[110:113], v10 offset:19712
	ds_read_b128 v[106:109], v10 offset:19456
	ds_read_b128 v[118:121], v10 offset:20224
	ds_read_b128 v[114:117], v10 offset:19968
	v_fma_mix_f32 v12, v6, v36, v180 op_sel_hi:[0,1,0]
	v_fma_mix_f32 v12, v7, v36, v12 op_sel:[0,1,0] op_sel_hi:[0,1,0]
	v_fma_mix_f32 v12, v8, v37, v12 op_sel_hi:[0,1,0]
	v_fma_mix_f32 v12, v9, v37, v12 op_sel:[0,1,0] op_sel_hi:[0,1,0]
	v_fma_mix_f32 v122, v6, v22, v180 op_sel_hi:[0,1,0]
	v_fma_mix_f32 v122, v7, v22, v122 op_sel:[0,1,0] op_sel_hi:[0,1,0]
	v_add_f32_dpp v12, v12, v12 row_ror:1 row_mask:0xf bank_mask:0xf bound_ctrl:1
	v_fma_mix_f32 v122, v8, v23, v122 op_sel_hi:[0,1,0]
	v_fma_mix_f32 v122, v9, v23, v122 op_sel:[0,1,0] op_sel_hi:[0,1,0]
	v_add_f32_dpp v12, v12, v12 row_ror:2 row_mask:0xf bank_mask:0xf bound_ctrl:1
	v_pk_fma_f32 v[48:49], v[44:45], v[66:67], v[6:7] op_sel:[0,1,0]
	v_pk_fma_f32 v[50:51], v[46:47], v[66:67], v[8:9] op_sel:[0,1,0]
	v_add_f32_dpp v12, v12, v12 row_ror:4 row_mask:0xf bank_mask:0xf bound_ctrl:1
	v_add_f32_dpp v83, v83, v83 row_ror:8 row_mask:0xf bank_mask:0xc
	v_add_f32_dpp v83, v52, v52 row_ror:8 row_mask:0xf bank_mask:0x3
	v_add_f32_dpp v100, v100, v100 row_ror:8 row_mask:0xf bank_mask:0xc
	v_add_f32_dpp v12, v12, v12 row_ror:8 row_mask:0xf bank_mask:0xf bound_ctrl:1
	v_pk_fma_f32 v[6:7], v[40:41], v[12:13], v[48:49] op_sel_hi:[1,0,1] neg_lo:[1,0,0] neg_hi:[1,0,0]
	v_pk_fma_f32 v[8:9], v[42:43], v[12:13], v[50:51] op_sel_hi:[1,0,1] neg_lo:[1,0,0] neg_hi:[1,0,0]
	ds_read_b128 v[142:145], v10 offset:20736
	ds_read_b128 v[150:153], v10 offset:21248
	ds_read_b128 v[146:149], v10 offset:20992
	ds_read_b128 v[70:73], v11 offset:1280
	s_waitcnt lgkmcnt(4)
	v_fma_mix_f32 v12, v6, v88, v180 op_sel_hi:[0,1,0]
	v_fma_mix_f32 v12, v7, v88, v12 op_sel:[0,1,0] op_sel_hi:[0,1,0]
	v_fma_mix_f32 v12, v8, v89, v12 op_sel_hi:[0,1,0]
	v_fma_mix_f32 v12, v9, v89, v12 op_sel:[0,1,0] op_sel_hi:[0,1,0]
	v_fma_mix_f32 v123, v6, v38, v180 op_sel_hi:[0,1,0]
	v_fma_mix_f32 v123, v7, v38, v123 op_sel:[0,1,0] op_sel_hi:[0,1,0]
	v_add_f32_dpp v12, v12, v12 row_ror:1 row_mask:0xf bank_mask:0xf bound_ctrl:1
	v_fma_mix_f32 v123, v8, v39, v123 op_sel_hi:[0,1,0]
	v_fma_mix_f32 v123, v9, v39, v123 op_sel:[0,1,0] op_sel_hi:[0,1,0]
	v_add_f32_dpp v12, v12, v12 row_ror:2 row_mask:0xf bank_mask:0xf bound_ctrl:1
	v_pk_fma_f32 v[48:49], v[96:97], v[68:69], v[6:7] op_sel_hi:[1,0,1]
	v_pk_fma_f32 v[50:51], v[98:99], v[68:69], v[8:9] op_sel_hi:[1,0,1]
	v_add_f32_dpp v12, v12, v12 row_ror:4 row_mask:0xf bank_mask:0xf bound_ctrl:1
	v_add_f32_dpp v100, v53, v53 row_ror:8 row_mask:0xf bank_mask:0x3
	v_add_f32_dpp v101, v101, v101 row_ror:8 row_mask:0xf bank_mask:0xc
	v_add_f32_dpp v101, v54, v54 row_ror:8 row_mask:0xf bank_mask:0x3
	v_add_f32_dpp v12, v12, v12 row_ror:8 row_mask:0xf bank_mask:0xf bound_ctrl:1
	v_pk_fma_f32 v[6:7], v[92:93], v[12:13], v[48:49] op_sel_hi:[1,0,1] neg_lo:[1,0,0] neg_hi:[1,0,0]
	v_pk_fma_f32 v[8:9], v[94:95], v[12:13], v[50:51] op_sel_hi:[1,0,1] neg_lo:[1,0,0] neg_hi:[1,0,0]
	ds_read_b128 v[158:161], v10 offset:21760
	ds_read_b128 v[166:169], v10 offset:22272
	ds_read_b128 v[162:165], v10 offset:22016
	v_fma_mix_f32 v12, v6, v110, v180 op_sel_hi:[0,1,0]
	v_fma_mix_f32 v12, v7, v110, v12 op_sel:[0,1,0] op_sel_hi:[0,1,0]
	v_fma_mix_f32 v12, v8, v111, v12 op_sel_hi:[0,1,0]
	v_fma_mix_f32 v12, v9, v111, v12 op_sel:[0,1,0] op_sel_hi:[0,1,0]
	v_fma_mix_f32 v124, v6, v90, v180 op_sel_hi:[0,1,0]
	v_fma_mix_f32 v124, v7, v90, v124 op_sel:[0,1,0] op_sel_hi:[0,1,0]
	v_add_f32_dpp v12, v12, v12 row_ror:1 row_mask:0xf bank_mask:0xf bound_ctrl:1
	v_fma_mix_f32 v124, v8, v91, v124 op_sel_hi:[0,1,0]
	v_fma_mix_f32 v124, v9, v91, v124 op_sel:[0,1,0] op_sel_hi:[0,1,0]
	v_add_f32_dpp v12, v12, v12 row_ror:2 row_mask:0xf bank_mask:0xf bound_ctrl:1
	v_pk_fma_f32 v[48:49], v[118:119], v[68:69], v[6:7] op_sel:[0,1,0]
	v_pk_fma_f32 v[50:51], v[120:121], v[68:69], v[8:9] op_sel:[0,1,0]
	v_add_f32_dpp v12, v12, v12 row_ror:4 row_mask:0xf bank_mask:0xf bound_ctrl:1
	v_add_f32_dpp v102, v102, v102 row_ror:8 row_mask:0xf bank_mask:0xc
	v_add_f32_dpp v102, v55, v55 row_ror:8 row_mask:0xf bank_mask:0x3
	v_add_f32_dpp v103, v103, v103 row_ror:8 row_mask:0xf bank_mask:0xc
	v_add_f32_dpp v12, v12, v12 row_ror:8 row_mask:0xf bank_mask:0xf bound_ctrl:1
	v_pk_fma_f32 v[6:7], v[114:115], v[12:13], v[48:49] op_sel_hi:[1,0,1] neg_lo:[1,0,0] neg_hi:[1,0,0]
	v_pk_fma_f32 v[8:9], v[116:117], v[12:13], v[50:51] op_sel_hi:[1,0,1] neg_lo:[1,0,0] neg_hi:[1,0,0]
	v_pk_mul_f32 v[6:7], v[6:7], v[106:107]
	v_pk_mul_f32 v[8:9], v[8:9], v[108:109]
	ds_read_b128 v[188:191], v10 offset:22784
	ds_read_b128 v[196:199], v10 offset:23296
	ds_read_b128 v[192:195], v10 offset:23040
	s_waitcnt lgkmcnt(3)
	v_fma_mix_f32 v12, v6, v142, v180 op_sel_hi:[0,1,0]
	v_fma_mix_f32 v12, v7, v142, v12 op_sel:[0,1,0] op_sel_hi:[0,1,0]
	v_fma_mix_f32 v12, v8, v143, v12 op_sel_hi:[0,1,0]
	v_fma_mix_f32 v12, v9, v143, v12 op_sel:[0,1,0] op_sel_hi:[0,1,0]
	v_fma_mix_f32 v125, v6, v112, v180 op_sel_hi:[0,1,0]
	v_fma_mix_f32 v125, v7, v112, v125 op_sel:[0,1,0] op_sel_hi:[0,1,0]
	v_add_f32_dpp v12, v12, v12 row_ror:1 row_mask:0xf bank_mask:0xf bound_ctrl:1
	v_fma_mix_f32 v125, v8, v113, v125 op_sel_hi:[0,1,0]
	v_fma_mix_f32 v125, v9, v113, v125 op_sel:[0,1,0] op_sel_hi:[0,1,0]
	v_add_f32_dpp v12, v12, v12 row_ror:2 row_mask:0xf bank_mask:0xf bound_ctrl:1
	v_pk_fma_f32 v[48:49], v[150:151], v[70:71], v[6:7] op_sel_hi:[1,0,1]
	v_pk_fma_f32 v[50:51], v[152:153], v[70:71], v[8:9] op_sel_hi:[1,0,1]
	v_add_f32_dpp v12, v12, v12 row_ror:4 row_mask:0xf bank_mask:0xf bound_ctrl:1
	v_add_f32_dpp v103, v56, v56 row_ror:8 row_mask:0xf bank_mask:0x3
	v_add_f32_dpp v104, v104, v104 row_ror:8 row_mask:0xf bank_mask:0xc
	v_add_f32_dpp v104, v57, v57 row_ror:8 row_mask:0xf bank_mask:0x3
	v_add_f32_dpp v12, v12, v12 row_ror:8 row_mask:0xf bank_mask:0xf bound_ctrl:1
	v_pk_fma_f32 v[6:7], v[146:147], v[12:13], v[48:49] op_sel_hi:[1,0,1] neg_lo:[1,0,0] neg_hi:[1,0,0]
	v_pk_fma_f32 v[8:9], v[148:149], v[12:13], v[50:51] op_sel_hi:[1,0,1] neg_lo:[1,0,0] neg_hi:[1,0,0]
	ds_read_b128 v[204:207], v10 offset:23808
	ds_read_b128 v[200:203], v10 offset:23552
	ds_read_b128 v[212:215], v10 offset:24320
	ds_read_b128 v[208:211], v10 offset:24064
	v_fma_mix_f32 v12, v6, v158, v180 op_sel_hi:[0,1,0]
	v_fma_mix_f32 v12, v7, v158, v12 op_sel:[0,1,0] op_sel_hi:[0,1,0]
	v_fma_mix_f32 v12, v8, v159, v12 op_sel_hi:[0,1,0]
	v_fma_mix_f32 v12, v9, v159, v12 op_sel:[0,1,0] op_sel_hi:[0,1,0]
	v_fma_mix_f32 v126, v6, v144, v180 op_sel_hi:[0,1,0]
	v_fma_mix_f32 v126, v7, v144, v126 op_sel:[0,1,0] op_sel_hi:[0,1,0]
	v_add_f32_dpp v12, v12, v12 row_ror:1 row_mask:0xf bank_mask:0xf bound_ctrl:1
	v_fma_mix_f32 v126, v8, v145, v126 op_sel_hi:[0,1,0]
	v_fma_mix_f32 v126, v9, v145, v126 op_sel:[0,1,0] op_sel_hi:[0,1,0]
	v_add_f32_dpp v12, v12, v12 row_ror:2 row_mask:0xf bank_mask:0xf bound_ctrl:1
	v_pk_fma_f32 v[48:49], v[166:167], v[70:71], v[6:7] op_sel:[0,1,0]
	v_pk_fma_f32 v[50:51], v[168:169], v[70:71], v[8:9] op_sel:[0,1,0]
	v_add_f32_dpp v12, v12, v12 row_ror:4 row_mask:0xf bank_mask:0xf bound_ctrl:1
	v_add_f32_dpp v105, v105, v105 row_ror:8 row_mask:0xf bank_mask:0xc
	v_add_f32_dpp v105, v81, v81 row_ror:8 row_mask:0xf bank_mask:0x3
	v_add_f32_dpp v12, v12, v12 row_ror:8 row_mask:0xf bank_mask:0xf bound_ctrl:1
	v_pk_fma_f32 v[6:7], v[162:163], v[12:13], v[48:49] op_sel_hi:[1,0,1] neg_lo:[1,0,0] neg_hi:[1,0,0]
	v_pk_fma_f32 v[8:9], v[164:165], v[12:13], v[50:51] op_sel_hi:[1,0,1] neg_lo:[1,0,0] neg_hi:[1,0,0]
	ds_read_b128 v[20:23], v10 offset:24832
	ds_read_b128 v[28:31], v10 offset:25344
	ds_read_b128 v[24:27], v10 offset:25088
	ds_read_b128 v[66:69], v11 offset:1536
	s_waitcnt lgkmcnt(4)
	v_fma_mix_f32 v12, v6, v188, v180 op_sel_hi:[0,1,0]
	v_fma_mix_f32 v12, v7, v188, v12 op_sel:[0,1,0] op_sel_hi:[0,1,0]
	v_fma_mix_f32 v12, v8, v189, v12 op_sel_hi:[0,1,0]
	v_fma_mix_f32 v12, v9, v189, v12 op_sel:[0,1,0] op_sel_hi:[0,1,0]
	v_fma_mix_f32 v127, v6, v160, v180 op_sel_hi:[0,1,0]
	v_fma_mix_f32 v127, v7, v160, v127 op_sel:[0,1,0] op_sel_hi:[0,1,0]
	v_add_f32_dpp v12, v12, v12 row_ror:1 row_mask:0xf bank_mask:0xf bound_ctrl:1
	v_fma_mix_f32 v127, v8, v161, v127 op_sel_hi:[0,1,0]
	v_fma_mix_f32 v127, v9, v161, v127 op_sel:[0,1,0] op_sel_hi:[0,1,0]
	v_add_f32_dpp v12, v12, v12 row_ror:2 row_mask:0xf bank_mask:0xf bound_ctrl:1
	v_pk_fma_f32 v[48:49], v[196:197], v[72:73], v[6:7] op_sel_hi:[1,0,1]
	v_pk_fma_f32 v[50:51], v[198:199], v[72:73], v[8:9] op_sel_hi:[1,0,1]
	v_add_f32_dpp v12, v12, v12 row_ror:4 row_mask:0xf bank_mask:0xf bound_ctrl:1
	v_add_f32_dpp v61, v61, v61 row_ror:8 row_mask:0xf bank_mask:0xc
	v_add_f32_dpp v61, v82, v82 row_ror:8 row_mask:0xf bank_mask:0x3
	v_add_f32_dpp v12, v12, v12 row_ror:8 row_mask:0xf bank_mask:0xf bound_ctrl:1
	v_pk_fma_f32 v[6:7], v[192:193], v[12:13], v[48:49] op_sel_hi:[1,0,1] neg_lo:[1,0,0] neg_hi:[1,0,0]
	v_pk_fma_f32 v[8:9], v[194:195], v[12:13], v[50:51] op_sel_hi:[1,0,1] neg_lo:[1,0,0] neg_hi:[1,0,0]
	ds_read_b128 v[36:39], v10 offset:25856
	ds_read_b128 v[44:47], v10 offset:26368
	ds_read_b128 v[40:43], v10 offset:26112
	v_fma_mix_f32 v12, v6, v204, v180 op_sel_hi:[0,1,0]
	v_fma_mix_f32 v12, v7, v204, v12 op_sel:[0,1,0] op_sel_hi:[0,1,0]
	v_fma_mix_f32 v12, v8, v205, v12 op_sel_hi:[0,1,0]
	v_fma_mix_f32 v12, v9, v205, v12 op_sel:[0,1,0] op_sel_hi:[0,1,0]
	v_fma_mix_f32 v128, v6, v190, v180 op_sel_hi:[0,1,0]
	v_fma_mix_f32 v128, v7, v190, v128 op_sel:[0,1,0] op_sel_hi:[0,1,0]
	v_add_f32_dpp v12, v12, v12 row_ror:1 row_mask:0xf bank_mask:0xf bound_ctrl:1
	v_fma_mix_f32 v128, v8, v191, v128 op_sel_hi:[0,1,0]
	v_fma_mix_f32 v128, v9, v191, v128 op_sel:[0,1,0] op_sel_hi:[0,1,0]
	v_add_f32_dpp v12, v12, v12 row_ror:2 row_mask:0xf bank_mask:0xf bound_ctrl:1
	v_pk_fma_f32 v[48:49], v[212:213], v[72:73], v[6:7] op_sel:[0,1,0]
	v_pk_fma_f32 v[50:51], v[214:215], v[72:73], v[8:9] op_sel:[0,1,0]
	v_add_f32_dpp v12, v12, v12 row_ror:4 row_mask:0xf bank_mask:0xf bound_ctrl:1
	v_add_f32_dpp v103, v103, v103 row_ror:4 row_mask:0xf bank_mask:0xa
	v_add_f32_dpp v103, v83, v83 row_ror:12 row_mask:0xf bank_mask:0x5
	v_add_f32_dpp v104, v104, v104 row_ror:4 row_mask:0xf bank_mask:0xa
	v_add_f32_dpp v12, v12, v12 row_ror:8 row_mask:0xf bank_mask:0xf bound_ctrl:1
	v_pk_fma_f32 v[6:7], v[208:209], v[12:13], v[48:49] op_sel_hi:[1,0,1] neg_lo:[1,0,0] neg_hi:[1,0,0]
	v_pk_fma_f32 v[8:9], v[210:211], v[12:13], v[50:51] op_sel_hi:[1,0,1] neg_lo:[1,0,0] neg_hi:[1,0,0]
	v_pk_mul_f32 v[6:7], v[6:7], v[200:201]
	v_pk_mul_f32 v[8:9], v[8:9], v[202:203]
	ds_read_b128 v[88:91], v10 offset:26880
	ds_read_b128 v[96:99], v10 offset:27392
	ds_read_b128 v[92:95], v10 offset:27136
	s_waitcnt lgkmcnt(3)
	v_fma_mix_f32 v12, v6, v20, v180 op_sel_hi:[0,1,0]
	v_fma_mix_f32 v12, v7, v20, v12 op_sel:[0,1,0] op_sel_hi:[0,1,0]
	v_fma_mix_f32 v12, v8, v21, v12 op_sel_hi:[0,1,0]
	v_fma_mix_f32 v12, v9, v21, v12 op_sel:[0,1,0] op_sel_hi:[0,1,0]
	v_fma_mix_f32 v129, v6, v206, v180 op_sel_hi:[0,1,0]
	v_fma_mix_f32 v129, v7, v206, v129 op_sel:[0,1,0] op_sel_hi:[0,1,0]
	v_add_f32_dpp v12, v12, v12 row_ror:1 row_mask:0xf bank_mask:0xf bound_ctrl:1
	v_fma_mix_f32 v129, v8, v207, v129 op_sel_hi:[0,1,0]
	v_fma_mix_f32 v129, v9, v207, v129 op_sel:[0,1,0] op_sel_hi:[0,1,0]
	v_add_f32_dpp v12, v12, v12 row_ror:2 row_mask:0xf bank_mask:0xf bound_ctrl:1
	v_pk_fma_f32 v[48:49], v[28:29], v[66:67], v[6:7] op_sel_hi:[1,0,1]
	v_pk_fma_f32 v[50:51], v[30:31], v[66:67], v[8:9] op_sel_hi:[1,0,1]
	v_add_f32_dpp v12, v12, v12 row_ror:4 row_mask:0xf bank_mask:0xf bound_ctrl:1
	v_add_f32_dpp v104, v100, v100 row_ror:12 row_mask:0xf bank_mask:0x5
	v_add_f32_dpp v105, v105, v105 row_ror:4 row_mask:0xf bank_mask:0xa
	v_add_f32_dpp v105, v101, v101 row_ror:12 row_mask:0xf bank_mask:0x5
	v_add_f32_dpp v12, v12, v12 row_ror:8 row_mask:0xf bank_mask:0xf bound_ctrl:1
	v_pk_fma_f32 v[6:7], v[24:25], v[12:13], v[48:49] op_sel_hi:[1,0,1] neg_lo:[1,0,0] neg_hi:[1,0,0]
	v_pk_fma_f32 v[8:9], v[26:27], v[12:13], v[50:51] op_sel_hi:[1,0,1] neg_lo:[1,0,0] neg_hi:[1,0,0]
	ds_read_b128 v[110:113], v10 offset:27904
	ds_read_b128 v[106:109], v10 offset:27648
	ds_read_b128 v[118:121], v10 offset:28416
	ds_read_b128 v[114:117], v10 offset:28160
	v_fma_mix_f32 v12, v6, v36, v180 op_sel_hi:[0,1,0]
	v_fma_mix_f32 v12, v7, v36, v12 op_sel:[0,1,0] op_sel_hi:[0,1,0]
	v_fma_mix_f32 v12, v8, v37, v12 op_sel_hi:[0,1,0]
	v_fma_mix_f32 v12, v9, v37, v12 op_sel:[0,1,0] op_sel_hi:[0,1,0]
	v_fma_mix_f32 v130, v6, v22, v180 op_sel_hi:[0,1,0]
	v_fma_mix_f32 v130, v7, v22, v130 op_sel:[0,1,0] op_sel_hi:[0,1,0]
	v_add_f32_dpp v12, v12, v12 row_ror:1 row_mask:0xf bank_mask:0xf bound_ctrl:1
	v_fma_mix_f32 v130, v8, v23, v130 op_sel_hi:[0,1,0]
	v_fma_mix_f32 v130, v9, v23, v130 op_sel:[0,1,0] op_sel_hi:[0,1,0]
	v_add_f32_dpp v12, v12, v12 row_ror:2 row_mask:0xf bank_mask:0xf bound_ctrl:1
	v_pk_fma_f32 v[48:49], v[44:45], v[66:67], v[6:7] op_sel:[0,1,0]
	v_pk_fma_f32 v[50:51], v[46:47], v[66:67], v[8:9] op_sel:[0,1,0]
	v_add_f32_dpp v12, v12, v12 row_ror:4 row_mask:0xf bank_mask:0xf bound_ctrl:1
	v_add_f32_dpp v61, v61, v61 row_ror:4 row_mask:0xf bank_mask:0xa
	v_add_f32_dpp v61, v102, v102 row_ror:12 row_mask:0xf bank_mask:0x5
	v_add_f32_dpp v12, v12, v12 row_ror:8 row_mask:0xf bank_mask:0xf bound_ctrl:1
	v_pk_fma_f32 v[6:7], v[40:41], v[12:13], v[48:49] op_sel_hi:[1,0,1] neg_lo:[1,0,0] neg_hi:[1,0,0]
	v_pk_fma_f32 v[8:9], v[42:43], v[12:13], v[50:51] op_sel_hi:[1,0,1] neg_lo:[1,0,0] neg_hi:[1,0,0]
	ds_read_b128 v[142:145], v10 offset:28928
	ds_read_b128 v[150:153], v10 offset:29440
	ds_read_b128 v[146:149], v10 offset:29184
	ds_read_b128 v[70:73], v11 offset:1792
	s_waitcnt lgkmcnt(4)
	v_fma_mix_f32 v12, v6, v88, v180 op_sel_hi:[0,1,0]
	v_fma_mix_f32 v12, v7, v88, v12 op_sel:[0,1,0] op_sel_hi:[0,1,0]
	v_fma_mix_f32 v12, v8, v89, v12 op_sel_hi:[0,1,0]
	v_fma_mix_f32 v12, v9, v89, v12 op_sel:[0,1,0] op_sel_hi:[0,1,0]
	v_fma_mix_f32 v131, v6, v38, v180 op_sel_hi:[0,1,0]
	v_fma_mix_f32 v131, v7, v38, v131 op_sel:[0,1,0] op_sel_hi:[0,1,0]
	v_add_f32_dpp v12, v12, v12 row_ror:1 row_mask:0xf bank_mask:0xf bound_ctrl:1
	v_fma_mix_f32 v131, v8, v39, v131 op_sel_hi:[0,1,0]
	v_fma_mix_f32 v131, v9, v39, v131 op_sel:[0,1,0] op_sel_hi:[0,1,0]
	v_add_f32_dpp v12, v12, v12 row_ror:2 row_mask:0xf bank_mask:0xf bound_ctrl:1
	v_pk_fma_f32 v[48:49], v[96:97], v[68:69], v[6:7] op_sel_hi:[1,0,1]
	v_pk_fma_f32 v[50:51], v[98:99], v[68:69], v[8:9] op_sel_hi:[1,0,1]
	v_add_f32_dpp v12, v12, v12 row_ror:4 row_mask:0xf bank_mask:0xf bound_ctrl:1
	v_cndmask_b32_e64 v62, v105, v103, s[38:39]
	v_cndmask_b32_e64 v63, v103, v105, s[38:39]
	v_add_f32_dpp v12, v12, v12 row_ror:8 row_mask:0xf bank_mask:0xf bound_ctrl:1
	v_pk_fma_f32 v[6:7], v[92:93], v[12:13], v[48:49] op_sel_hi:[1,0,1] neg_lo:[1,0,0] neg_hi:[1,0,0]
	v_pk_fma_f32 v[8:9], v[94:95], v[12:13], v[50:51] op_sel_hi:[1,0,1] neg_lo:[1,0,0] neg_hi:[1,0,0]
	ds_read_b128 v[158:161], v10 offset:29952
	ds_read_b128 v[166:169], v10 offset:30464
	ds_read_b128 v[162:165], v10 offset:30208
	v_fma_mix_f32 v12, v6, v110, v180 op_sel_hi:[0,1,0]
	v_fma_mix_f32 v12, v7, v110, v12 op_sel:[0,1,0] op_sel_hi:[0,1,0]
	v_fma_mix_f32 v12, v8, v111, v12 op_sel_hi:[0,1,0]
	v_fma_mix_f32 v12, v9, v111, v12 op_sel:[0,1,0] op_sel_hi:[0,1,0]
	v_fma_mix_f32 v132, v6, v90, v180 op_sel_hi:[0,1,0]
	v_fma_mix_f32 v132, v7, v90, v132 op_sel:[0,1,0] op_sel_hi:[0,1,0]
	v_add_f32_dpp v12, v12, v12 row_ror:1 row_mask:0xf bank_mask:0xf bound_ctrl:1
	v_fma_mix_f32 v132, v8, v91, v132 op_sel_hi:[0,1,0]
	v_fma_mix_f32 v132, v9, v91, v132 op_sel:[0,1,0] op_sel_hi:[0,1,0]
	v_add_f32_dpp v12, v12, v12 row_ror:2 row_mask:0xf bank_mask:0xf bound_ctrl:1
	v_pk_fma_f32 v[48:49], v[118:119], v[68:69], v[6:7] op_sel:[0,1,0]
	v_pk_fma_f32 v[50:51], v[120:121], v[68:69], v[8:9] op_sel:[0,1,0]
	v_add_f32_dpp v12, v12, v12 row_ror:4 row_mask:0xf bank_mask:0xf bound_ctrl:1
	v_cndmask_b32_e64 v64, v61, v104, s[38:39]
	v_cndmask_b32_e64 v65, v104, v61, s[38:39]
	v_add_f32_dpp v12, v12, v12 row_ror:8 row_mask:0xf bank_mask:0xf bound_ctrl:1
	v_pk_fma_f32 v[6:7], v[114:115], v[12:13], v[48:49] op_sel_hi:[1,0,1] neg_lo:[1,0,0] neg_hi:[1,0,0]
	v_pk_fma_f32 v[8:9], v[116:117], v[12:13], v[50:51] op_sel_hi:[1,0,1] neg_lo:[1,0,0] neg_hi:[1,0,0]
	v_pk_mul_f32 v[6:7], v[6:7], v[106:107]
	v_pk_mul_f32 v[8:9], v[8:9], v[108:109]
	ds_read_b128 v[188:191], v10 offset:30976
	ds_read_b128 v[196:199], v10 offset:31488
	ds_read_b128 v[192:195], v10 offset:31232
	s_waitcnt lgkmcnt(3)
	v_fma_mix_f32 v12, v6, v142, v180 op_sel_hi:[0,1,0]
	v_fma_mix_f32 v12, v7, v142, v12 op_sel:[0,1,0] op_sel_hi:[0,1,0]
	v_fma_mix_f32 v12, v8, v143, v12 op_sel_hi:[0,1,0]
	v_fma_mix_f32 v12, v9, v143, v12 op_sel:[0,1,0] op_sel_hi:[0,1,0]
	v_fma_mix_f32 v133, v6, v112, v180 op_sel_hi:[0,1,0]
	v_fma_mix_f32 v133, v7, v112, v133 op_sel:[0,1,0] op_sel_hi:[0,1,0]
	v_add_f32_dpp v12, v12, v12 row_ror:1 row_mask:0xf bank_mask:0xf bound_ctrl:1
	v_fma_mix_f32 v133, v8, v113, v133 op_sel_hi:[0,1,0]
	v_fma_mix_f32 v133, v9, v113, v133 op_sel:[0,1,0] op_sel_hi:[0,1,0]
	v_add_f32_dpp v12, v12, v12 row_ror:2 row_mask:0xf bank_mask:0xf bound_ctrl:1
	v_pk_fma_f32 v[48:49], v[150:151], v[70:71], v[6:7] op_sel_hi:[1,0,1]
	v_pk_fma_f32 v[50:51], v[152:153], v[70:71], v[8:9] op_sel_hi:[1,0,1]
	v_add_f32_dpp v12, v12, v12 row_ror:4 row_mask:0xf bank_mask:0xf bound_ctrl:1
	v_add_f32_dpp v62, v63, v62 quad_perm:[2,3,0,1] row_mask:0xf bank_mask:0xf bound_ctrl:1
	v_add_f32_dpp v63, v65, v64 quad_perm:[2,3,0,1] row_mask:0xf bank_mask:0xf bound_ctrl:1
	v_add_f32_dpp v12, v12, v12 row_ror:8 row_mask:0xf bank_mask:0xf bound_ctrl:1
	v_pk_fma_f32 v[6:7], v[146:147], v[12:13], v[48:49] op_sel_hi:[1,0,1] neg_lo:[1,0,0] neg_hi:[1,0,0]
	v_pk_fma_f32 v[8:9], v[148:149], v[12:13], v[50:51] op_sel_hi:[1,0,1] neg_lo:[1,0,0] neg_hi:[1,0,0]
	ds_read_b128 v[204:207], v10 offset:32000
	ds_read_b128 v[200:203], v10 offset:31744
	ds_read_b128 v[212:215], v10 offset:32512
	ds_read_b128 v[208:211], v10 offset:32256
	v_fma_mix_f32 v12, v6, v158, v180 op_sel_hi:[0,1,0]
	v_fma_mix_f32 v12, v7, v158, v12 op_sel:[0,1,0] op_sel_hi:[0,1,0]
	v_fma_mix_f32 v12, v8, v159, v12 op_sel_hi:[0,1,0]
	v_fma_mix_f32 v12, v9, v159, v12 op_sel:[0,1,0] op_sel_hi:[0,1,0]
	v_fma_mix_f32 v134, v6, v144, v180 op_sel_hi:[0,1,0]
	v_fma_mix_f32 v134, v7, v144, v134 op_sel:[0,1,0] op_sel_hi:[0,1,0]
	v_add_f32_dpp v12, v12, v12 row_ror:1 row_mask:0xf bank_mask:0xf bound_ctrl:1
	v_fma_mix_f32 v134, v8, v145, v134 op_sel_hi:[0,1,0]
	v_fma_mix_f32 v134, v9, v145, v134 op_sel:[0,1,0] op_sel_hi:[0,1,0]
	v_add_f32_dpp v12, v12, v12 row_ror:2 row_mask:0xf bank_mask:0xf bound_ctrl:1
	v_pk_fma_f32 v[48:49], v[166:167], v[70:71], v[6:7] op_sel:[0,1,0]
	v_pk_fma_f32 v[50:51], v[168:169], v[70:71], v[8:9] op_sel:[0,1,0]
	v_add_f32_dpp v12, v12, v12 row_ror:4 row_mask:0xf bank_mask:0xf bound_ctrl:1
	v_cndmask_b32_e64 v65, v63, v62, s[40:41]
	v_cndmask_b32_e64 v62, v62, v63, s[40:41]
	v_add_f32_dpp v12, v12, v12 row_ror:8 row_mask:0xf bank_mask:0xf bound_ctrl:1
	v_pk_fma_f32 v[6:7], v[162:163], v[12:13], v[48:49] op_sel_hi:[1,0,1] neg_lo:[1,0,0] neg_hi:[1,0,0]
	v_pk_fma_f32 v[8:9], v[164:165], v[12:13], v[50:51] op_sel_hi:[1,0,1] neg_lo:[1,0,0] neg_hi:[1,0,0]
	ds_read_b128 v[20:23], v10 offset:33024
	ds_read_b128 v[28:31], v10 offset:33536
	ds_read_b128 v[24:27], v10 offset:33280
	ds_read_b128 v[66:69], v11 offset:2048
	s_waitcnt lgkmcnt(4)
	v_fma_mix_f32 v12, v6, v188, v180 op_sel_hi:[0,1,0]
	v_fma_mix_f32 v12, v7, v188, v12 op_sel:[0,1,0] op_sel_hi:[0,1,0]
	v_fma_mix_f32 v12, v8, v189, v12 op_sel_hi:[0,1,0]
	v_fma_mix_f32 v12, v9, v189, v12 op_sel:[0,1,0] op_sel_hi:[0,1,0]
	v_fma_mix_f32 v135, v6, v160, v180 op_sel_hi:[0,1,0]
	v_fma_mix_f32 v135, v7, v160, v135 op_sel:[0,1,0] op_sel_hi:[0,1,0]
	v_add_f32_dpp v12, v12, v12 row_ror:1 row_mask:0xf bank_mask:0xf bound_ctrl:1
	v_fma_mix_f32 v135, v8, v161, v135 op_sel_hi:[0,1,0]
	v_fma_mix_f32 v135, v9, v161, v135 op_sel:[0,1,0] op_sel_hi:[0,1,0]
	v_add_f32_dpp v12, v12, v12 row_ror:2 row_mask:0xf bank_mask:0xf bound_ctrl:1
	v_pk_fma_f32 v[48:49], v[196:197], v[72:73], v[6:7] op_sel_hi:[1,0,1]
	v_pk_fma_f32 v[50:51], v[198:199], v[72:73], v[8:9] op_sel_hi:[1,0,1]
	v_add_f32_dpp v12, v12, v12 row_ror:4 row_mask:0xf bank_mask:0xf bound_ctrl:1
	v_add_f32_dpp v62, v62, v65 quad_perm:[1,0,3,2] row_mask:0xf bank_mask:0xf bound_ctrl:1
	v_cvt_pk_bf16_f32 v62, v62, v62
	v_add_f32_dpp v12, v12, v12 row_ror:8 row_mask:0xf bank_mask:0xf bound_ctrl:1
	v_pk_fma_f32 v[6:7], v[192:193], v[12:13], v[48:49] op_sel_hi:[1,0,1] neg_lo:[1,0,0] neg_hi:[1,0,0]
	v_pk_fma_f32 v[8:9], v[194:195], v[12:13], v[50:51] op_sel_hi:[1,0,1] neg_lo:[1,0,0] neg_hi:[1,0,0]
	ds_read_b128 v[36:39], v10 offset:34048
	ds_read_b128 v[44:47], v10 offset:34560
	ds_read_b128 v[40:43], v10 offset:34304
	v_fma_mix_f32 v12, v6, v204, v180 op_sel_hi:[0,1,0]
	v_fma_mix_f32 v12, v7, v204, v12 op_sel:[0,1,0] op_sel_hi:[0,1,0]
	v_fma_mix_f32 v12, v8, v205, v12 op_sel_hi:[0,1,0]
	v_fma_mix_f32 v12, v9, v205, v12 op_sel:[0,1,0] op_sel_hi:[0,1,0]
	v_fma_mix_f32 v136, v6, v190, v180 op_sel_hi:[0,1,0]
	v_fma_mix_f32 v136, v7, v190, v136 op_sel:[0,1,0] op_sel_hi:[0,1,0]
	v_add_f32_dpp v12, v12, v12 row_ror:1 row_mask:0xf bank_mask:0xf bound_ctrl:1
	v_fma_mix_f32 v136, v8, v191, v136 op_sel_hi:[0,1,0]
	v_fma_mix_f32 v136, v9, v191, v136 op_sel:[0,1,0] op_sel_hi:[0,1,0]
	v_add_f32_dpp v12, v12, v12 row_ror:2 row_mask:0xf bank_mask:0xf bound_ctrl:1
	v_pk_fma_f32 v[48:49], v[212:213], v[72:73], v[6:7] op_sel:[0,1,0]
	v_pk_fma_f32 v[50:51], v[214:215], v[72:73], v[8:9] op_sel:[0,1,0]
	v_add_f32_dpp v12, v12, v12 row_ror:4 row_mask:0xf bank_mask:0xf bound_ctrl:1
	global_store_short v[2:3], v62, off
	v_lshl_add_u64 v[2:3], v[2:3], 0, s[84:85]
	v_add_f32_dpp v12, v12, v12 row_ror:8 row_mask:0xf bank_mask:0xf bound_ctrl:1
	v_pk_fma_f32 v[6:7], v[208:209], v[12:13], v[48:49] op_sel_hi:[1,0,1] neg_lo:[1,0,0] neg_hi:[1,0,0]
	v_pk_fma_f32 v[8:9], v[210:211], v[12:13], v[50:51] op_sel_hi:[1,0,1] neg_lo:[1,0,0] neg_hi:[1,0,0]
	v_pk_mul_f32 v[6:7], v[6:7], v[200:201]
	v_pk_mul_f32 v[8:9], v[8:9], v[202:203]
	ds_read_b128 v[88:91], v10 offset:35072
	ds_read_b128 v[96:99], v10 offset:35584
	ds_read_b128 v[92:95], v10 offset:35328
	s_waitcnt lgkmcnt(3)
	v_fma_mix_f32 v12, v6, v20, v180 op_sel_hi:[0,1,0]
	v_fma_mix_f32 v12, v7, v20, v12 op_sel:[0,1,0] op_sel_hi:[0,1,0]
	v_fma_mix_f32 v12, v8, v21, v12 op_sel_hi:[0,1,0]
	v_fma_mix_f32 v12, v9, v21, v12 op_sel:[0,1,0] op_sel_hi:[0,1,0]
	v_fma_mix_f32 v137, v6, v206, v180 op_sel_hi:[0,1,0]
	v_fma_mix_f32 v137, v7, v206, v137 op_sel:[0,1,0] op_sel_hi:[0,1,0]
	v_add_f32_dpp v12, v12, v12 row_ror:1 row_mask:0xf bank_mask:0xf bound_ctrl:1
	v_fma_mix_f32 v137, v8, v207, v137 op_sel_hi:[0,1,0]
	v_fma_mix_f32 v137, v9, v207, v137 op_sel:[0,1,0] op_sel_hi:[0,1,0]
	v_add_f32_dpp v12, v12, v12 row_ror:2 row_mask:0xf bank_mask:0xf bound_ctrl:1
	v_pk_fma_f32 v[48:49], v[28:29], v[66:67], v[6:7] op_sel_hi:[1,0,1]
	v_pk_fma_f32 v[50:51], v[30:31], v[66:67], v[8:9] op_sel_hi:[1,0,1]
	v_add_f32_dpp v12, v12, v12 row_ror:4 row_mask:0xf bank_mask:0xf bound_ctrl:1
	s_nop 1
	v_add_f32_dpp v12, v12, v12 row_ror:8 row_mask:0xf bank_mask:0xf bound_ctrl:1
	v_pk_fma_f32 v[6:7], v[24:25], v[12:13], v[48:49] op_sel_hi:[1,0,1] neg_lo:[1,0,0] neg_hi:[1,0,0]
	v_pk_fma_f32 v[8:9], v[26:27], v[12:13], v[50:51] op_sel_hi:[1,0,1] neg_lo:[1,0,0] neg_hi:[1,0,0]
	ds_read_b128 v[110:113], v10 offset:36096
	ds_read_b128 v[106:109], v10 offset:35840
	ds_read_b128 v[118:121], v10 offset:36608
	ds_read_b128 v[114:117], v10 offset:36352
	v_fma_mix_f32 v12, v6, v36, v180 op_sel_hi:[0,1,0]
	v_fma_mix_f32 v12, v7, v36, v12 op_sel:[0,1,0] op_sel_hi:[0,1,0]
	v_fma_mix_f32 v12, v8, v37, v12 op_sel_hi:[0,1,0]
	v_fma_mix_f32 v12, v9, v37, v12 op_sel:[0,1,0] op_sel_hi:[0,1,0]
	v_fma_mix_f32 v52, v6, v22, v180 op_sel_hi:[0,1,0]
	v_fma_mix_f32 v52, v7, v22, v52 op_sel:[0,1,0] op_sel_hi:[0,1,0]
	v_add_f32_dpp v12, v12, v12 row_ror:1 row_mask:0xf bank_mask:0xf bound_ctrl:1
	v_fma_mix_f32 v52, v8, v23, v52 op_sel_hi:[0,1,0]
	v_fma_mix_f32 v52, v9, v23, v52 op_sel:[0,1,0] op_sel_hi:[0,1,0]
	v_add_f32_dpp v12, v12, v12 row_ror:2 row_mask:0xf bank_mask:0xf bound_ctrl:1
	v_pk_fma_f32 v[48:49], v[44:45], v[66:67], v[6:7] op_sel:[0,1,0]
	v_pk_fma_f32 v[50:51], v[46:47], v[66:67], v[8:9] op_sel:[0,1,0]
	v_add_f32_dpp v12, v12, v12 row_ror:4 row_mask:0xf bank_mask:0xf bound_ctrl:1
	v_add_f32_dpp v130, v130, v130 row_ror:8 row_mask:0xf bank_mask:0xc
	v_add_f32_dpp v130, v122, v122 row_ror:8 row_mask:0xf bank_mask:0x3
	v_add_f32_dpp v131, v131, v131 row_ror:8 row_mask:0xf bank_mask:0xc
	v_add_f32_dpp v12, v12, v12 row_ror:8 row_mask:0xf bank_mask:0xf bound_ctrl:1
	v_pk_fma_f32 v[6:7], v[40:41], v[12:13], v[48:49] op_sel_hi:[1,0,1] neg_lo:[1,0,0] neg_hi:[1,0,0]
	v_pk_fma_f32 v[8:9], v[42:43], v[12:13], v[50:51] op_sel_hi:[1,0,1] neg_lo:[1,0,0] neg_hi:[1,0,0]
	ds_read_b128 v[142:145], v10 offset:37120
	ds_read_b128 v[150:153], v10 offset:37632
	ds_read_b128 v[146:149], v10 offset:37376
	ds_read_b128 v[70:73], v11 offset:2304
	s_waitcnt lgkmcnt(4)
	v_fma_mix_f32 v12, v6, v88, v180 op_sel_hi:[0,1,0]
	v_fma_mix_f32 v12, v7, v88, v12 op_sel:[0,1,0] op_sel_hi:[0,1,0]
	v_fma_mix_f32 v12, v8, v89, v12 op_sel_hi:[0,1,0]
	v_fma_mix_f32 v12, v9, v89, v12 op_sel:[0,1,0] op_sel_hi:[0,1,0]
	v_fma_mix_f32 v53, v6, v38, v180 op_sel_hi:[0,1,0]
	v_fma_mix_f32 v53, v7, v38, v53 op_sel:[0,1,0] op_sel_hi:[0,1,0]
	v_add_f32_dpp v12, v12, v12 row_ror:1 row_mask:0xf bank_mask:0xf bound_ctrl:1
	v_fma_mix_f32 v53, v8, v39, v53 op_sel_hi:[0,1,0]
	v_fma_mix_f32 v53, v9, v39, v53 op_sel:[0,1,0] op_sel_hi:[0,1,0]
	v_add_f32_dpp v12, v12, v12 row_ror:2 row_mask:0xf bank_mask:0xf bound_ctrl:1
	v_pk_fma_f32 v[48:49], v[96:97], v[68:69], v[6:7] op_sel_hi:[1,0,1]
	v_pk_fma_f32 v[50:51], v[98:99], v[68:69], v[8:9] op_sel_hi:[1,0,1]
	v_add_f32_dpp v12, v12, v12 row_ror:4 row_mask:0xf bank_mask:0xf bound_ctrl:1
	v_add_f32_dpp v131, v123, v123 row_ror:8 row_mask:0xf bank_mask:0x3
	v_add_f32_dpp v132, v132, v132 row_ror:8 row_mask:0xf bank_mask:0xc
	v_add_f32_dpp v132, v124, v124 row_ror:8 row_mask:0xf bank_mask:0x3
	v_add_f32_dpp v12, v12, v12 row_ror:8 row_mask:0xf bank_mask:0xf bound_ctrl:1
	v_pk_fma_f32 v[6:7], v[92:93], v[12:13], v[48:49] op_sel_hi:[1,0,1] neg_lo:[1,0,0] neg_hi:[1,0,0]
	v_pk_fma_f32 v[8:9], v[94:95], v[12:13], v[50:51] op_sel_hi:[1,0,1] neg_lo:[1,0,0] neg_hi:[1,0,0]
	ds_read_b128 v[158:161], v10 offset:38144
	ds_read_b128 v[166:169], v10 offset:38656
	ds_read_b128 v[162:165], v10 offset:38400
	v_fma_mix_f32 v12, v6, v110, v180 op_sel_hi:[0,1,0]
	v_fma_mix_f32 v12, v7, v110, v12 op_sel:[0,1,0] op_sel_hi:[0,1,0]
	v_fma_mix_f32 v12, v8, v111, v12 op_sel_hi:[0,1,0]
	v_fma_mix_f32 v12, v9, v111, v12 op_sel:[0,1,0] op_sel_hi:[0,1,0]
	v_fma_mix_f32 v54, v6, v90, v180 op_sel_hi:[0,1,0]
	v_fma_mix_f32 v54, v7, v90, v54 op_sel:[0,1,0] op_sel_hi:[0,1,0]
	v_add_f32_dpp v12, v12, v12 row_ror:1 row_mask:0xf bank_mask:0xf bound_ctrl:1
	v_fma_mix_f32 v54, v8, v91, v54 op_sel_hi:[0,1,0]
	v_fma_mix_f32 v54, v9, v91, v54 op_sel:[0,1,0] op_sel_hi:[0,1,0]
	v_add_f32_dpp v12, v12, v12 row_ror:2 row_mask:0xf bank_mask:0xf bound_ctrl:1
	v_pk_fma_f32 v[48:49], v[118:119], v[68:69], v[6:7] op_sel:[0,1,0]
	v_pk_fma_f32 v[50:51], v[120:121], v[68:69], v[8:9] op_sel:[0,1,0]
	v_add_f32_dpp v12, v12, v12 row_ror:4 row_mask:0xf bank_mask:0xf bound_ctrl:1
	v_add_f32_dpp v133, v133, v133 row_ror:8 row_mask:0xf bank_mask:0xc
	v_add_f32_dpp v133, v125, v125 row_ror:8 row_mask:0xf bank_mask:0x3
	v_add_f32_dpp v134, v134, v134 row_ror:8 row_mask:0xf bank_mask:0xc
	v_add_f32_dpp v12, v12, v12 row_ror:8 row_mask:0xf bank_mask:0xf bound_ctrl:1
	v_pk_fma_f32 v[6:7], v[114:115], v[12:13], v[48:49] op_sel_hi:[1,0,1] neg_lo:[1,0,0] neg_hi:[1,0,0]
	v_pk_fma_f32 v[8:9], v[116:117], v[12:13], v[50:51] op_sel_hi:[1,0,1] neg_lo:[1,0,0] neg_hi:[1,0,0]
	v_pk_mul_f32 v[6:7], v[6:7], v[106:107]
	v_pk_mul_f32 v[8:9], v[8:9], v[108:109]
	ds_read_b128 v[188:191], v10 offset:39168
	ds_read_b128 v[196:199], v10 offset:39680
	ds_read_b128 v[192:195], v10 offset:39424
	s_waitcnt lgkmcnt(3)
	v_fma_mix_f32 v12, v6, v142, v180 op_sel_hi:[0,1,0]
	v_fma_mix_f32 v12, v7, v142, v12 op_sel:[0,1,0] op_sel_hi:[0,1,0]
	v_fma_mix_f32 v12, v8, v143, v12 op_sel_hi:[0,1,0]
	v_fma_mix_f32 v12, v9, v143, v12 op_sel:[0,1,0] op_sel_hi:[0,1,0]
	v_fma_mix_f32 v55, v6, v112, v180 op_sel_hi:[0,1,0]
	v_fma_mix_f32 v55, v7, v112, v55 op_sel:[0,1,0] op_sel_hi:[0,1,0]
	v_add_f32_dpp v12, v12, v12 row_ror:1 row_mask:0xf bank_mask:0xf bound_ctrl:1
	v_fma_mix_f32 v55, v8, v113, v55 op_sel_hi:[0,1,0]
	v_fma_mix_f32 v55, v9, v113, v55 op_sel:[0,1,0] op_sel_hi:[0,1,0]
	v_add_f32_dpp v12, v12, v12 row_ror:2 row_mask:0xf bank_mask:0xf bound_ctrl:1
	v_pk_fma_f32 v[48:49], v[150:151], v[70:71], v[6:7] op_sel_hi:[1,0,1]
	v_pk_fma_f32 v[50:51], v[152:153], v[70:71], v[8:9] op_sel_hi:[1,0,1]
	v_add_f32_dpp v12, v12, v12 row_ror:4 row_mask:0xf bank_mask:0xf bound_ctrl:1
	v_add_f32_dpp v134, v126, v126 row_ror:8 row_mask:0xf bank_mask:0x3
	v_add_f32_dpp v135, v135, v135 row_ror:8 row_mask:0xf bank_mask:0xc
	v_add_f32_dpp v135, v127, v127 row_ror:8 row_mask:0xf bank_mask:0x3
	v_add_f32_dpp v12, v12, v12 row_ror:8 row_mask:0xf bank_mask:0xf bound_ctrl:1
	v_pk_fma_f32 v[6:7], v[146:147], v[12:13], v[48:49] op_sel_hi:[1,0,1] neg_lo:[1,0,0] neg_hi:[1,0,0]
	v_pk_fma_f32 v[8:9], v[148:149], v[12:13], v[50:51] op_sel_hi:[1,0,1] neg_lo:[1,0,0] neg_hi:[1,0,0]
	ds_read_b128 v[204:207], v10 offset:40192
	ds_read_b128 v[200:203], v10 offset:39936
	ds_read_b128 v[212:215], v10 offset:40704
	ds_read_b128 v[208:211], v10 offset:40448
	v_fma_mix_f32 v12, v6, v158, v180 op_sel_hi:[0,1,0]
	v_fma_mix_f32 v12, v7, v158, v12 op_sel:[0,1,0] op_sel_hi:[0,1,0]
	v_fma_mix_f32 v12, v8, v159, v12 op_sel_hi:[0,1,0]
	v_fma_mix_f32 v12, v9, v159, v12 op_sel:[0,1,0] op_sel_hi:[0,1,0]
	v_fma_mix_f32 v56, v6, v144, v180 op_sel_hi:[0,1,0]
	v_fma_mix_f32 v56, v7, v144, v56 op_sel:[0,1,0] op_sel_hi:[0,1,0]
	v_add_f32_dpp v12, v12, v12 row_ror:1 row_mask:0xf bank_mask:0xf bound_ctrl:1
	v_fma_mix_f32 v56, v8, v145, v56 op_sel_hi:[0,1,0]
	v_fma_mix_f32 v56, v9, v145, v56 op_sel:[0,1,0] op_sel_hi:[0,1,0]
	v_add_f32_dpp v12, v12, v12 row_ror:2 row_mask:0xf bank_mask:0xf bound_ctrl:1
	v_pk_fma_f32 v[48:49], v[166:167], v[70:71], v[6:7] op_sel:[0,1,0]
	v_pk_fma_f32 v[50:51], v[168:169], v[70:71], v[8:9] op_sel:[0,1,0]
	v_add_f32_dpp v12, v12, v12 row_ror:4 row_mask:0xf bank_mask:0xf bound_ctrl:1
	v_add_f32_dpp v136, v136, v136 row_ror:8 row_mask:0xf bank_mask:0xc
	v_add_f32_dpp v136, v128, v128 row_ror:8 row_mask:0xf bank_mask:0x3
	v_add_f32_dpp v12, v12, v12 row_ror:8 row_mask:0xf bank_mask:0xf bound_ctrl:1
	v_pk_fma_f32 v[6:7], v[162:163], v[12:13], v[48:49] op_sel_hi:[1,0,1] neg_lo:[1,0,0] neg_hi:[1,0,0]
	v_pk_fma_f32 v[8:9], v[164:165], v[12:13], v[50:51] op_sel_hi:[1,0,1] neg_lo:[1,0,0] neg_hi:[1,0,0]
	ds_read_b128 v[20:23], v10 offset:41216
	ds_read_b128 v[28:31], v10 offset:41728
	ds_read_b128 v[24:27], v10 offset:41472
	ds_read_b128 v[66:69], v11 offset:2560
	s_waitcnt lgkmcnt(4)
	v_fma_mix_f32 v12, v6, v188, v180 op_sel_hi:[0,1,0]
	v_fma_mix_f32 v12, v7, v188, v12 op_sel:[0,1,0] op_sel_hi:[0,1,0]
	v_fma_mix_f32 v12, v8, v189, v12 op_sel_hi:[0,1,0]
	v_fma_mix_f32 v12, v9, v189, v12 op_sel:[0,1,0] op_sel_hi:[0,1,0]
	v_fma_mix_f32 v57, v6, v160, v180 op_sel_hi:[0,1,0]
	v_fma_mix_f32 v57, v7, v160, v57 op_sel:[0,1,0] op_sel_hi:[0,1,0]
	v_add_f32_dpp v12, v12, v12 row_ror:1 row_mask:0xf bank_mask:0xf bound_ctrl:1
	v_fma_mix_f32 v57, v8, v161, v57 op_sel_hi:[0,1,0]
	v_fma_mix_f32 v57, v9, v161, v57 op_sel:[0,1,0] op_sel_hi:[0,1,0]
	v_add_f32_dpp v12, v12, v12 row_ror:2 row_mask:0xf bank_mask:0xf bound_ctrl:1
	v_pk_fma_f32 v[48:49], v[196:197], v[72:73], v[6:7] op_sel_hi:[1,0,1]
	v_pk_fma_f32 v[50:51], v[198:199], v[72:73], v[8:9] op_sel_hi:[1,0,1]
	v_add_f32_dpp v12, v12, v12 row_ror:4 row_mask:0xf bank_mask:0xf bound_ctrl:1
	v_add_f32_dpp v137, v137, v137 row_ror:8 row_mask:0xf bank_mask:0xc
	v_add_f32_dpp v137, v129, v129 row_ror:8 row_mask:0xf bank_mask:0x3
	v_add_f32_dpp v12, v12, v12 row_ror:8 row_mask:0xf bank_mask:0xf bound_ctrl:1
	v_pk_fma_f32 v[6:7], v[192:193], v[12:13], v[48:49] op_sel_hi:[1,0,1] neg_lo:[1,0,0] neg_hi:[1,0,0]
	v_pk_fma_f32 v[8:9], v[194:195], v[12:13], v[50:51] op_sel_hi:[1,0,1] neg_lo:[1,0,0] neg_hi:[1,0,0]
	ds_read_b128 v[36:39], v10 offset:42240
	ds_read_b128 v[44:47], v10 offset:42752
	ds_read_b128 v[40:43], v10 offset:42496
	v_fma_mix_f32 v12, v6, v204, v180 op_sel_hi:[0,1,0]
	v_fma_mix_f32 v12, v7, v204, v12 op_sel:[0,1,0] op_sel_hi:[0,1,0]
	v_fma_mix_f32 v12, v8, v205, v12 op_sel_hi:[0,1,0]
	v_fma_mix_f32 v12, v9, v205, v12 op_sel:[0,1,0] op_sel_hi:[0,1,0]
	v_fma_mix_f32 v81, v6, v190, v180 op_sel_hi:[0,1,0]
	v_fma_mix_f32 v81, v7, v190, v81 op_sel:[0,1,0] op_sel_hi:[0,1,0]
	v_add_f32_dpp v12, v12, v12 row_ror:1 row_mask:0xf bank_mask:0xf bound_ctrl:1
	v_fma_mix_f32 v81, v8, v191, v81 op_sel_hi:[0,1,0]
	v_fma_mix_f32 v81, v9, v191, v81 op_sel:[0,1,0] op_sel_hi:[0,1,0]
	v_add_f32_dpp v12, v12, v12 row_ror:2 row_mask:0xf bank_mask:0xf bound_ctrl:1
	v_pk_fma_f32 v[48:49], v[212:213], v[72:73], v[6:7] op_sel:[0,1,0]
	v_pk_fma_f32 v[50:51], v[214:215], v[72:73], v[8:9] op_sel:[0,1,0]
	v_add_f32_dpp v12, v12, v12 row_ror:4 row_mask:0xf bank_mask:0xf bound_ctrl:1
	v_add_f32_dpp v134, v134, v134 row_ror:4 row_mask:0xf bank_mask:0xa
	v_add_f32_dpp v134, v130, v130 row_ror:12 row_mask:0xf bank_mask:0x5
	v_add_f32_dpp v135, v135, v135 row_ror:4 row_mask:0xf bank_mask:0xa
	v_add_f32_dpp v12, v12, v12 row_ror:8 row_mask:0xf bank_mask:0xf bound_ctrl:1
	v_pk_fma_f32 v[6:7], v[208:209], v[12:13], v[48:49] op_sel_hi:[1,0,1] neg_lo:[1,0,0] neg_hi:[1,0,0]
	v_pk_fma_f32 v[8:9], v[210:211], v[12:13], v[50:51] op_sel_hi:[1,0,1] neg_lo:[1,0,0] neg_hi:[1,0,0]
	v_pk_mul_f32 v[6:7], v[6:7], v[200:201]
	v_pk_mul_f32 v[8:9], v[8:9], v[202:203]
	ds_read_b128 v[88:91], v10 offset:43264
	ds_read_b128 v[96:99], v10 offset:43776
	ds_read_b128 v[92:95], v10 offset:43520
	s_waitcnt lgkmcnt(3)
	v_fma_mix_f32 v12, v6, v20, v180 op_sel_hi:[0,1,0]
	v_fma_mix_f32 v12, v7, v20, v12 op_sel:[0,1,0] op_sel_hi:[0,1,0]
	v_fma_mix_f32 v12, v8, v21, v12 op_sel_hi:[0,1,0]
	v_fma_mix_f32 v12, v9, v21, v12 op_sel:[0,1,0] op_sel_hi:[0,1,0]
	v_fma_mix_f32 v82, v6, v206, v180 op_sel_hi:[0,1,0]
	v_fma_mix_f32 v82, v7, v206, v82 op_sel:[0,1,0] op_sel_hi:[0,1,0]
	v_add_f32_dpp v12, v12, v12 row_ror:1 row_mask:0xf bank_mask:0xf bound_ctrl:1
	v_fma_mix_f32 v82, v8, v207, v82 op_sel_hi:[0,1,0]
	v_fma_mix_f32 v82, v9, v207, v82 op_sel:[0,1,0] op_sel_hi:[0,1,0]
	v_add_f32_dpp v12, v12, v12 row_ror:2 row_mask:0xf bank_mask:0xf bound_ctrl:1
	v_pk_fma_f32 v[48:49], v[28:29], v[66:67], v[6:7] op_sel_hi:[1,0,1]
	v_pk_fma_f32 v[50:51], v[30:31], v[66:67], v[8:9] op_sel_hi:[1,0,1]
	v_add_f32_dpp v12, v12, v12 row_ror:4 row_mask:0xf bank_mask:0xf bound_ctrl:1
	v_add_f32_dpp v135, v131, v131 row_ror:12 row_mask:0xf bank_mask:0x5
	v_add_f32_dpp v136, v136, v136 row_ror:4 row_mask:0xf bank_mask:0xa
	v_add_f32_dpp v136, v132, v132 row_ror:12 row_mask:0xf bank_mask:0x5
	v_add_f32_dpp v12, v12, v12 row_ror:8 row_mask:0xf bank_mask:0xf bound_ctrl:1
	v_pk_fma_f32 v[6:7], v[24:25], v[12:13], v[48:49] op_sel_hi:[1,0,1] neg_lo:[1,0,0] neg_hi:[1,0,0]
	v_pk_fma_f32 v[8:9], v[26:27], v[12:13], v[50:51] op_sel_hi:[1,0,1] neg_lo:[1,0,0] neg_hi:[1,0,0]
	ds_read_b128 v[110:113], v10 offset:44288
	ds_read_b128 v[106:109], v10 offset:44032
	ds_read_b128 v[118:121], v10 offset:44800
	ds_read_b128 v[114:117], v10 offset:44544
	v_fma_mix_f32 v12, v6, v36, v180 op_sel_hi:[0,1,0]
	v_fma_mix_f32 v12, v7, v36, v12 op_sel:[0,1,0] op_sel_hi:[0,1,0]
	v_fma_mix_f32 v12, v8, v37, v12 op_sel_hi:[0,1,0]
	v_fma_mix_f32 v12, v9, v37, v12 op_sel:[0,1,0] op_sel_hi:[0,1,0]
	v_fma_mix_f32 v83, v6, v22, v180 op_sel_hi:[0,1,0]
	v_fma_mix_f32 v83, v7, v22, v83 op_sel:[0,1,0] op_sel_hi:[0,1,0]
	v_add_f32_dpp v12, v12, v12 row_ror:1 row_mask:0xf bank_mask:0xf bound_ctrl:1
	v_fma_mix_f32 v83, v8, v23, v83 op_sel_hi:[0,1,0]
	v_fma_mix_f32 v83, v9, v23, v83 op_sel:[0,1,0] op_sel_hi:[0,1,0]
	v_add_f32_dpp v12, v12, v12 row_ror:2 row_mask:0xf bank_mask:0xf bound_ctrl:1
	v_pk_fma_f32 v[48:49], v[44:45], v[66:67], v[6:7] op_sel:[0,1,0]
	v_pk_fma_f32 v[50:51], v[46:47], v[66:67], v[8:9] op_sel:[0,1,0]
	v_add_f32_dpp v12, v12, v12 row_ror:4 row_mask:0xf bank_mask:0xf bound_ctrl:1
	v_add_f32_dpp v137, v137, v137 row_ror:4 row_mask:0xf bank_mask:0xa
	v_add_f32_dpp v137, v133, v133 row_ror:12 row_mask:0xf bank_mask:0x5
	v_add_f32_dpp v12, v12, v12 row_ror:8 row_mask:0xf bank_mask:0xf bound_ctrl:1
	v_pk_fma_f32 v[6:7], v[40:41], v[12:13], v[48:49] op_sel_hi:[1,0,1] neg_lo:[1,0,0] neg_hi:[1,0,0]
	v_pk_fma_f32 v[8:9], v[42:43], v[12:13], v[50:51] op_sel_hi:[1,0,1] neg_lo:[1,0,0] neg_hi:[1,0,0]
	ds_read_b128 v[142:145], v10 offset:45312
	ds_read_b128 v[150:153], v10 offset:45824
	ds_read_b128 v[146:149], v10 offset:45568
	ds_read_b128 v[70:73], v11 offset:2816
	s_waitcnt lgkmcnt(4)
	v_fma_mix_f32 v12, v6, v88, v180 op_sel_hi:[0,1,0]
	v_fma_mix_f32 v12, v7, v88, v12 op_sel:[0,1,0] op_sel_hi:[0,1,0]
	v_fma_mix_f32 v12, v8, v89, v12 op_sel_hi:[0,1,0]
	v_fma_mix_f32 v12, v9, v89, v12 op_sel:[0,1,0] op_sel_hi:[0,1,0]
	v_fma_mix_f32 v100, v6, v38, v180 op_sel_hi:[0,1,0]
	v_fma_mix_f32 v100, v7, v38, v100 op_sel:[0,1,0] op_sel_hi:[0,1,0]
	v_add_f32_dpp v12, v12, v12 row_ror:1 row_mask:0xf bank_mask:0xf bound_ctrl:1
	v_fma_mix_f32 v100, v8, v39, v100 op_sel_hi:[0,1,0]
	v_fma_mix_f32 v100, v9, v39, v100 op_sel:[0,1,0] op_sel_hi:[0,1,0]
	v_add_f32_dpp v12, v12, v12 row_ror:2 row_mask:0xf bank_mask:0xf bound_ctrl:1
	v_pk_fma_f32 v[48:49], v[96:97], v[68:69], v[6:7] op_sel_hi:[1,0,1]
	v_pk_fma_f32 v[50:51], v[98:99], v[68:69], v[8:9] op_sel_hi:[1,0,1]
	v_add_f32_dpp v12, v12, v12 row_ror:4 row_mask:0xf bank_mask:0xf bound_ctrl:1
	v_cndmask_b32_e64 v62, v136, v134, s[38:39]
	v_cndmask_b32_e64 v63, v134, v136, s[38:39]
	v_add_f32_dpp v12, v12, v12 row_ror:8 row_mask:0xf bank_mask:0xf bound_ctrl:1
	v_pk_fma_f32 v[6:7], v[92:93], v[12:13], v[48:49] op_sel_hi:[1,0,1] neg_lo:[1,0,0] neg_hi:[1,0,0]
	v_pk_fma_f32 v[8:9], v[94:95], v[12:13], v[50:51] op_sel_hi:[1,0,1] neg_lo:[1,0,0] neg_hi:[1,0,0]
	ds_read_b128 v[158:161], v10 offset:46336
	ds_read_b128 v[166:169], v10 offset:46848
	ds_read_b128 v[162:165], v10 offset:46592
	v_fma_mix_f32 v12, v6, v110, v180 op_sel_hi:[0,1,0]
	v_fma_mix_f32 v12, v7, v110, v12 op_sel:[0,1,0] op_sel_hi:[0,1,0]
	v_fma_mix_f32 v12, v8, v111, v12 op_sel_hi:[0,1,0]
	v_fma_mix_f32 v12, v9, v111, v12 op_sel:[0,1,0] op_sel_hi:[0,1,0]
	v_fma_mix_f32 v101, v6, v90, v180 op_sel_hi:[0,1,0]
	v_fma_mix_f32 v101, v7, v90, v101 op_sel:[0,1,0] op_sel_hi:[0,1,0]
	v_add_f32_dpp v12, v12, v12 row_ror:1 row_mask:0xf bank_mask:0xf bound_ctrl:1
	v_fma_mix_f32 v101, v8, v91, v101 op_sel_hi:[0,1,0]
	v_fma_mix_f32 v101, v9, v91, v101 op_sel:[0,1,0] op_sel_hi:[0,1,0]
	v_add_f32_dpp v12, v12, v12 row_ror:2 row_mask:0xf bank_mask:0xf bound_ctrl:1
	v_pk_fma_f32 v[48:49], v[118:119], v[68:69], v[6:7] op_sel:[0,1,0]
	v_pk_fma_f32 v[50:51], v[120:121], v[68:69], v[8:9] op_sel:[0,1,0]
	v_add_f32_dpp v12, v12, v12 row_ror:4 row_mask:0xf bank_mask:0xf bound_ctrl:1
	v_cndmask_b32_e64 v64, v137, v135, s[38:39]
	v_cndmask_b32_e64 v65, v135, v137, s[38:39]
	v_add_f32_dpp v12, v12, v12 row_ror:8 row_mask:0xf bank_mask:0xf bound_ctrl:1
	v_pk_fma_f32 v[6:7], v[114:115], v[12:13], v[48:49] op_sel_hi:[1,0,1] neg_lo:[1,0,0] neg_hi:[1,0,0]
	v_pk_fma_f32 v[8:9], v[116:117], v[12:13], v[50:51] op_sel_hi:[1,0,1] neg_lo:[1,0,0] neg_hi:[1,0,0]
	v_pk_mul_f32 v[6:7], v[6:7], v[106:107]
	v_pk_mul_f32 v[8:9], v[8:9], v[108:109]
	ds_read_b128 v[188:191], v10 offset:47360
	ds_read_b128 v[196:199], v10 offset:47872
	ds_read_b128 v[192:195], v10 offset:47616
	s_waitcnt lgkmcnt(3)
	v_fma_mix_f32 v12, v6, v142, v180 op_sel_hi:[0,1,0]
	v_fma_mix_f32 v12, v7, v142, v12 op_sel:[0,1,0] op_sel_hi:[0,1,0]
	v_fma_mix_f32 v12, v8, v143, v12 op_sel_hi:[0,1,0]
	v_fma_mix_f32 v12, v9, v143, v12 op_sel:[0,1,0] op_sel_hi:[0,1,0]
	v_fma_mix_f32 v102, v6, v112, v180 op_sel_hi:[0,1,0]
	v_fma_mix_f32 v102, v7, v112, v102 op_sel:[0,1,0] op_sel_hi:[0,1,0]
	v_add_f32_dpp v12, v12, v12 row_ror:1 row_mask:0xf bank_mask:0xf bound_ctrl:1
	v_fma_mix_f32 v102, v8, v113, v102 op_sel_hi:[0,1,0]
	v_fma_mix_f32 v102, v9, v113, v102 op_sel:[0,1,0] op_sel_hi:[0,1,0]
	v_add_f32_dpp v12, v12, v12 row_ror:2 row_mask:0xf bank_mask:0xf bound_ctrl:1
	v_pk_fma_f32 v[48:49], v[150:151], v[70:71], v[6:7] op_sel_hi:[1,0,1]
	v_pk_fma_f32 v[50:51], v[152:153], v[70:71], v[8:9] op_sel_hi:[1,0,1]
	v_add_f32_dpp v12, v12, v12 row_ror:4 row_mask:0xf bank_mask:0xf bound_ctrl:1
	v_add_f32_dpp v62, v63, v62 quad_perm:[2,3,0,1] row_mask:0xf bank_mask:0xf bound_ctrl:1
	v_add_f32_dpp v63, v65, v64 quad_perm:[2,3,0,1] row_mask:0xf bank_mask:0xf bound_ctrl:1
	v_add_f32_dpp v12, v12, v12 row_ror:8 row_mask:0xf bank_mask:0xf bound_ctrl:1
	v_pk_fma_f32 v[6:7], v[146:147], v[12:13], v[48:49] op_sel_hi:[1,0,1] neg_lo:[1,0,0] neg_hi:[1,0,0]
	v_pk_fma_f32 v[8:9], v[148:149], v[12:13], v[50:51] op_sel_hi:[1,0,1] neg_lo:[1,0,0] neg_hi:[1,0,0]
	ds_read_b128 v[204:207], v10 offset:48384
	ds_read_b128 v[200:203], v10 offset:48128
	ds_read_b128 v[212:215], v10 offset:48896
	ds_read_b128 v[208:211], v10 offset:48640
	v_fma_mix_f32 v12, v6, v158, v180 op_sel_hi:[0,1,0]
	v_fma_mix_f32 v12, v7, v158, v12 op_sel:[0,1,0] op_sel_hi:[0,1,0]
	v_fma_mix_f32 v12, v8, v159, v12 op_sel_hi:[0,1,0]
	v_fma_mix_f32 v12, v9, v159, v12 op_sel:[0,1,0] op_sel_hi:[0,1,0]
	v_fma_mix_f32 v103, v6, v144, v180 op_sel_hi:[0,1,0]
	v_fma_mix_f32 v103, v7, v144, v103 op_sel:[0,1,0] op_sel_hi:[0,1,0]
	v_add_f32_dpp v12, v12, v12 row_ror:1 row_mask:0xf bank_mask:0xf bound_ctrl:1
	v_fma_mix_f32 v103, v8, v145, v103 op_sel_hi:[0,1,0]
	v_fma_mix_f32 v103, v9, v145, v103 op_sel:[0,1,0] op_sel_hi:[0,1,0]
	v_add_f32_dpp v12, v12, v12 row_ror:2 row_mask:0xf bank_mask:0xf bound_ctrl:1
	v_pk_fma_f32 v[48:49], v[166:167], v[70:71], v[6:7] op_sel:[0,1,0]
	v_pk_fma_f32 v[50:51], v[168:169], v[70:71], v[8:9] op_sel:[0,1,0]
	v_add_f32_dpp v12, v12, v12 row_ror:4 row_mask:0xf bank_mask:0xf bound_ctrl:1
	v_cndmask_b32_e64 v65, v63, v62, s[40:41]
	v_cndmask_b32_e64 v62, v62, v63, s[40:41]
	v_add_f32_dpp v12, v12, v12 row_ror:8 row_mask:0xf bank_mask:0xf bound_ctrl:1
	v_pk_fma_f32 v[6:7], v[162:163], v[12:13], v[48:49] op_sel_hi:[1,0,1] neg_lo:[1,0,0] neg_hi:[1,0,0]
	v_pk_fma_f32 v[8:9], v[164:165], v[12:13], v[50:51] op_sel_hi:[1,0,1] neg_lo:[1,0,0] neg_hi:[1,0,0]
	ds_read_b128 v[20:23], v10 offset:49408
	ds_read_b128 v[28:31], v10 offset:49920
	ds_read_b128 v[24:27], v10 offset:49664
	ds_read_b128 v[66:69], v11 offset:3072
	s_waitcnt lgkmcnt(4)
	v_fma_mix_f32 v12, v6, v188, v180 op_sel_hi:[0,1,0]
	v_fma_mix_f32 v12, v7, v188, v12 op_sel:[0,1,0] op_sel_hi:[0,1,0]
	v_fma_mix_f32 v12, v8, v189, v12 op_sel_hi:[0,1,0]
	v_fma_mix_f32 v12, v9, v189, v12 op_sel:[0,1,0] op_sel_hi:[0,1,0]
	v_fma_mix_f32 v104, v6, v160, v180 op_sel_hi:[0,1,0]
	v_fma_mix_f32 v104, v7, v160, v104 op_sel:[0,1,0] op_sel_hi:[0,1,0]
	v_add_f32_dpp v12, v12, v12 row_ror:1 row_mask:0xf bank_mask:0xf bound_ctrl:1
	v_fma_mix_f32 v104, v8, v161, v104 op_sel_hi:[0,1,0]
	v_fma_mix_f32 v104, v9, v161, v104 op_sel:[0,1,0] op_sel_hi:[0,1,0]
	v_add_f32_dpp v12, v12, v12 row_ror:2 row_mask:0xf bank_mask:0xf bound_ctrl:1
	v_pk_fma_f32 v[48:49], v[196:197], v[72:73], v[6:7] op_sel_hi:[1,0,1]
	v_pk_fma_f32 v[50:51], v[198:199], v[72:73], v[8:9] op_sel_hi:[1,0,1]
	v_add_f32_dpp v12, v12, v12 row_ror:4 row_mask:0xf bank_mask:0xf bound_ctrl:1
	v_add_f32_dpp v62, v62, v65 quad_perm:[1,0,3,2] row_mask:0xf bank_mask:0xf bound_ctrl:1
	v_cvt_pk_bf16_f32 v62, v62, v62
	v_add_f32_dpp v12, v12, v12 row_ror:8 row_mask:0xf bank_mask:0xf bound_ctrl:1
	v_pk_fma_f32 v[6:7], v[192:193], v[12:13], v[48:49] op_sel_hi:[1,0,1] neg_lo:[1,0,0] neg_hi:[1,0,0]
	v_pk_fma_f32 v[8:9], v[194:195], v[12:13], v[50:51] op_sel_hi:[1,0,1] neg_lo:[1,0,0] neg_hi:[1,0,0]
	ds_read_b128 v[36:39], v10 offset:50432
	ds_read_b128 v[44:47], v10 offset:50944
	ds_read_b128 v[40:43], v10 offset:50688
	v_fma_mix_f32 v12, v6, v204, v180 op_sel_hi:[0,1,0]
	v_fma_mix_f32 v12, v7, v204, v12 op_sel:[0,1,0] op_sel_hi:[0,1,0]
	v_fma_mix_f32 v12, v8, v205, v12 op_sel_hi:[0,1,0]
	v_fma_mix_f32 v12, v9, v205, v12 op_sel:[0,1,0] op_sel_hi:[0,1,0]
	v_fma_mix_f32 v105, v6, v190, v180 op_sel_hi:[0,1,0]
	v_fma_mix_f32 v105, v7, v190, v105 op_sel:[0,1,0] op_sel_hi:[0,1,0]
	v_add_f32_dpp v12, v12, v12 row_ror:1 row_mask:0xf bank_mask:0xf bound_ctrl:1
	v_fma_mix_f32 v105, v8, v191, v105 op_sel_hi:[0,1,0]
	v_fma_mix_f32 v105, v9, v191, v105 op_sel:[0,1,0] op_sel_hi:[0,1,0]
	v_add_f32_dpp v12, v12, v12 row_ror:2 row_mask:0xf bank_mask:0xf bound_ctrl:1
	v_pk_fma_f32 v[48:49], v[212:213], v[72:73], v[6:7] op_sel:[0,1,0]
	v_pk_fma_f32 v[50:51], v[214:215], v[72:73], v[8:9] op_sel:[0,1,0]
	v_add_f32_dpp v12, v12, v12 row_ror:4 row_mask:0xf bank_mask:0xf bound_ctrl:1
	global_store_short v[2:3], v62, off
	v_lshl_add_u64 v[2:3], v[2:3], 0, s[84:85]
	v_add_f32_dpp v12, v12, v12 row_ror:8 row_mask:0xf bank_mask:0xf bound_ctrl:1
	v_pk_fma_f32 v[6:7], v[208:209], v[12:13], v[48:49] op_sel_hi:[1,0,1] neg_lo:[1,0,0] neg_hi:[1,0,0]
	v_pk_fma_f32 v[8:9], v[210:211], v[12:13], v[50:51] op_sel_hi:[1,0,1] neg_lo:[1,0,0] neg_hi:[1,0,0]
	v_pk_mul_f32 v[6:7], v[6:7], v[200:201]
	v_pk_mul_f32 v[8:9], v[8:9], v[202:203]
	ds_read_b128 v[88:91], v10 offset:51456
	ds_read_b128 v[96:99], v10 offset:51968
	ds_read_b128 v[92:95], v10 offset:51712
	s_waitcnt lgkmcnt(3)
	v_fma_mix_f32 v12, v6, v20, v180 op_sel_hi:[0,1,0]
	v_fma_mix_f32 v12, v7, v20, v12 op_sel:[0,1,0] op_sel_hi:[0,1,0]
	v_fma_mix_f32 v12, v8, v21, v12 op_sel_hi:[0,1,0]
	v_fma_mix_f32 v12, v9, v21, v12 op_sel:[0,1,0] op_sel_hi:[0,1,0]
	v_fma_mix_f32 v61, v6, v206, v180 op_sel_hi:[0,1,0]
	v_fma_mix_f32 v61, v7, v206, v61 op_sel:[0,1,0] op_sel_hi:[0,1,0]
	v_add_f32_dpp v12, v12, v12 row_ror:1 row_mask:0xf bank_mask:0xf bound_ctrl:1
	v_fma_mix_f32 v61, v8, v207, v61 op_sel_hi:[0,1,0]
	v_fma_mix_f32 v61, v9, v207, v61 op_sel:[0,1,0] op_sel_hi:[0,1,0]
	v_add_f32_dpp v12, v12, v12 row_ror:2 row_mask:0xf bank_mask:0xf bound_ctrl:1
	v_pk_fma_f32 v[48:49], v[28:29], v[66:67], v[6:7] op_sel_hi:[1,0,1]
	v_pk_fma_f32 v[50:51], v[30:31], v[66:67], v[8:9] op_sel_hi:[1,0,1]
	v_add_f32_dpp v12, v12, v12 row_ror:4 row_mask:0xf bank_mask:0xf bound_ctrl:1
	s_nop 1
	v_add_f32_dpp v12, v12, v12 row_ror:8 row_mask:0xf bank_mask:0xf bound_ctrl:1
	v_pk_fma_f32 v[6:7], v[24:25], v[12:13], v[48:49] op_sel_hi:[1,0,1] neg_lo:[1,0,0] neg_hi:[1,0,0]
	v_pk_fma_f32 v[8:9], v[26:27], v[12:13], v[50:51] op_sel_hi:[1,0,1] neg_lo:[1,0,0] neg_hi:[1,0,0]
	ds_read_b128 v[110:113], v10 offset:52480
	ds_read_b128 v[106:109], v10 offset:52224
	ds_read_b128 v[118:121], v10 offset:52992
	ds_read_b128 v[114:117], v10 offset:52736
	v_fma_mix_f32 v12, v6, v36, v180 op_sel_hi:[0,1,0]
	v_fma_mix_f32 v12, v7, v36, v12 op_sel:[0,1,0] op_sel_hi:[0,1,0]
	v_fma_mix_f32 v12, v8, v37, v12 op_sel_hi:[0,1,0]
	v_fma_mix_f32 v12, v9, v37, v12 op_sel:[0,1,0] op_sel_hi:[0,1,0]
	v_fma_mix_f32 v122, v6, v22, v180 op_sel_hi:[0,1,0]
	v_fma_mix_f32 v122, v7, v22, v122 op_sel:[0,1,0] op_sel_hi:[0,1,0]
	v_add_f32_dpp v12, v12, v12 row_ror:1 row_mask:0xf bank_mask:0xf bound_ctrl:1
	v_fma_mix_f32 v122, v8, v23, v122 op_sel_hi:[0,1,0]
	v_fma_mix_f32 v122, v9, v23, v122 op_sel:[0,1,0] op_sel_hi:[0,1,0]
	v_add_f32_dpp v12, v12, v12 row_ror:2 row_mask:0xf bank_mask:0xf bound_ctrl:1
	v_pk_fma_f32 v[48:49], v[44:45], v[66:67], v[6:7] op_sel:[0,1,0]
	v_pk_fma_f32 v[50:51], v[46:47], v[66:67], v[8:9] op_sel:[0,1,0]
	v_add_f32_dpp v12, v12, v12 row_ror:4 row_mask:0xf bank_mask:0xf bound_ctrl:1
	v_add_f32_dpp v83, v83, v83 row_ror:8 row_mask:0xf bank_mask:0xc
	v_add_f32_dpp v83, v52, v52 row_ror:8 row_mask:0xf bank_mask:0x3
	v_add_f32_dpp v100, v100, v100 row_ror:8 row_mask:0xf bank_mask:0xc
	v_add_f32_dpp v12, v12, v12 row_ror:8 row_mask:0xf bank_mask:0xf bound_ctrl:1
	v_pk_fma_f32 v[6:7], v[40:41], v[12:13], v[48:49] op_sel_hi:[1,0,1] neg_lo:[1,0,0] neg_hi:[1,0,0]
	v_pk_fma_f32 v[8:9], v[42:43], v[12:13], v[50:51] op_sel_hi:[1,0,1] neg_lo:[1,0,0] neg_hi:[1,0,0]
	ds_read_b128 v[142:145], v10 offset:53504
	ds_read_b128 v[150:153], v10 offset:54016
	ds_read_b128 v[146:149], v10 offset:53760
	ds_read_b128 v[70:73], v11 offset:3328
	s_waitcnt lgkmcnt(4)
	v_fma_mix_f32 v12, v6, v88, v180 op_sel_hi:[0,1,0]
	v_fma_mix_f32 v12, v7, v88, v12 op_sel:[0,1,0] op_sel_hi:[0,1,0]
	v_fma_mix_f32 v12, v8, v89, v12 op_sel_hi:[0,1,0]
	v_fma_mix_f32 v12, v9, v89, v12 op_sel:[0,1,0] op_sel_hi:[0,1,0]
	v_fma_mix_f32 v123, v6, v38, v180 op_sel_hi:[0,1,0]
	v_fma_mix_f32 v123, v7, v38, v123 op_sel:[0,1,0] op_sel_hi:[0,1,0]
	v_add_f32_dpp v12, v12, v12 row_ror:1 row_mask:0xf bank_mask:0xf bound_ctrl:1
	v_fma_mix_f32 v123, v8, v39, v123 op_sel_hi:[0,1,0]
	v_fma_mix_f32 v123, v9, v39, v123 op_sel:[0,1,0] op_sel_hi:[0,1,0]
	v_add_f32_dpp v12, v12, v12 row_ror:2 row_mask:0xf bank_mask:0xf bound_ctrl:1
	v_pk_fma_f32 v[48:49], v[96:97], v[68:69], v[6:7] op_sel_hi:[1,0,1]
	v_pk_fma_f32 v[50:51], v[98:99], v[68:69], v[8:9] op_sel_hi:[1,0,1]
	v_add_f32_dpp v12, v12, v12 row_ror:4 row_mask:0xf bank_mask:0xf bound_ctrl:1
	v_add_f32_dpp v100, v53, v53 row_ror:8 row_mask:0xf bank_mask:0x3
	v_add_f32_dpp v101, v101, v101 row_ror:8 row_mask:0xf bank_mask:0xc
	v_add_f32_dpp v101, v54, v54 row_ror:8 row_mask:0xf bank_mask:0x3
	v_add_f32_dpp v12, v12, v12 row_ror:8 row_mask:0xf bank_mask:0xf bound_ctrl:1
	v_pk_fma_f32 v[6:7], v[92:93], v[12:13], v[48:49] op_sel_hi:[1,0,1] neg_lo:[1,0,0] neg_hi:[1,0,0]
	v_pk_fma_f32 v[8:9], v[94:95], v[12:13], v[50:51] op_sel_hi:[1,0,1] neg_lo:[1,0,0] neg_hi:[1,0,0]
	ds_read_b128 v[158:161], v10 offset:54528
	ds_read_b128 v[166:169], v10 offset:55040
	ds_read_b128 v[162:165], v10 offset:54784
	v_fma_mix_f32 v12, v6, v110, v180 op_sel_hi:[0,1,0]
	v_fma_mix_f32 v12, v7, v110, v12 op_sel:[0,1,0] op_sel_hi:[0,1,0]
	v_fma_mix_f32 v12, v8, v111, v12 op_sel_hi:[0,1,0]
	v_fma_mix_f32 v12, v9, v111, v12 op_sel:[0,1,0] op_sel_hi:[0,1,0]
	v_fma_mix_f32 v124, v6, v90, v180 op_sel_hi:[0,1,0]
	v_fma_mix_f32 v124, v7, v90, v124 op_sel:[0,1,0] op_sel_hi:[0,1,0]
	v_add_f32_dpp v12, v12, v12 row_ror:1 row_mask:0xf bank_mask:0xf bound_ctrl:1
	v_fma_mix_f32 v124, v8, v91, v124 op_sel_hi:[0,1,0]
	v_fma_mix_f32 v124, v9, v91, v124 op_sel:[0,1,0] op_sel_hi:[0,1,0]
	v_add_f32_dpp v12, v12, v12 row_ror:2 row_mask:0xf bank_mask:0xf bound_ctrl:1
	v_pk_fma_f32 v[48:49], v[118:119], v[68:69], v[6:7] op_sel:[0,1,0]
	v_pk_fma_f32 v[50:51], v[120:121], v[68:69], v[8:9] op_sel:[0,1,0]
	v_add_f32_dpp v12, v12, v12 row_ror:4 row_mask:0xf bank_mask:0xf bound_ctrl:1
	v_add_f32_dpp v102, v102, v102 row_ror:8 row_mask:0xf bank_mask:0xc
	v_add_f32_dpp v102, v55, v55 row_ror:8 row_mask:0xf bank_mask:0x3
	v_add_f32_dpp v103, v103, v103 row_ror:8 row_mask:0xf bank_mask:0xc
	v_add_f32_dpp v12, v12, v12 row_ror:8 row_mask:0xf bank_mask:0xf bound_ctrl:1
	v_pk_fma_f32 v[6:7], v[114:115], v[12:13], v[48:49] op_sel_hi:[1,0,1] neg_lo:[1,0,0] neg_hi:[1,0,0]
	v_pk_fma_f32 v[8:9], v[116:117], v[12:13], v[50:51] op_sel_hi:[1,0,1] neg_lo:[1,0,0] neg_hi:[1,0,0]
	v_pk_mul_f32 v[6:7], v[6:7], v[106:107]
	v_pk_mul_f32 v[8:9], v[8:9], v[108:109]
	ds_read_b128 v[188:191], v10 offset:55552
	ds_read_b128 v[196:199], v10 offset:56064
	ds_read_b128 v[192:195], v10 offset:55808
	s_waitcnt lgkmcnt(3)
	v_fma_mix_f32 v12, v6, v142, v180 op_sel_hi:[0,1,0]
	v_fma_mix_f32 v12, v7, v142, v12 op_sel:[0,1,0] op_sel_hi:[0,1,0]
	v_fma_mix_f32 v12, v8, v143, v12 op_sel_hi:[0,1,0]
	v_fma_mix_f32 v12, v9, v143, v12 op_sel:[0,1,0] op_sel_hi:[0,1,0]
	v_fma_mix_f32 v125, v6, v112, v180 op_sel_hi:[0,1,0]
	v_fma_mix_f32 v125, v7, v112, v125 op_sel:[0,1,0] op_sel_hi:[0,1,0]
	v_add_f32_dpp v12, v12, v12 row_ror:1 row_mask:0xf bank_mask:0xf bound_ctrl:1
	v_fma_mix_f32 v125, v8, v113, v125 op_sel_hi:[0,1,0]
	v_fma_mix_f32 v125, v9, v113, v125 op_sel:[0,1,0] op_sel_hi:[0,1,0]
	v_add_f32_dpp v12, v12, v12 row_ror:2 row_mask:0xf bank_mask:0xf bound_ctrl:1
	v_pk_fma_f32 v[48:49], v[150:151], v[70:71], v[6:7] op_sel_hi:[1,0,1]
	v_pk_fma_f32 v[50:51], v[152:153], v[70:71], v[8:9] op_sel_hi:[1,0,1]
	v_add_f32_dpp v12, v12, v12 row_ror:4 row_mask:0xf bank_mask:0xf bound_ctrl:1
	v_add_f32_dpp v103, v56, v56 row_ror:8 row_mask:0xf bank_mask:0x3
	v_add_f32_dpp v104, v104, v104 row_ror:8 row_mask:0xf bank_mask:0xc
	v_add_f32_dpp v104, v57, v57 row_ror:8 row_mask:0xf bank_mask:0x3
	v_add_f32_dpp v12, v12, v12 row_ror:8 row_mask:0xf bank_mask:0xf bound_ctrl:1
	v_pk_fma_f32 v[6:7], v[146:147], v[12:13], v[48:49] op_sel_hi:[1,0,1] neg_lo:[1,0,0] neg_hi:[1,0,0]
	v_pk_fma_f32 v[8:9], v[148:149], v[12:13], v[50:51] op_sel_hi:[1,0,1] neg_lo:[1,0,0] neg_hi:[1,0,0]
	ds_read_b128 v[204:207], v10 offset:56576
	ds_read_b128 v[200:203], v10 offset:56320
	ds_read_b128 v[212:215], v10 offset:57088
	ds_read_b128 v[208:211], v10 offset:56832
	v_fma_mix_f32 v12, v6, v158, v180 op_sel_hi:[0,1,0]
	v_fma_mix_f32 v12, v7, v158, v12 op_sel:[0,1,0] op_sel_hi:[0,1,0]
	v_fma_mix_f32 v12, v8, v159, v12 op_sel_hi:[0,1,0]
	v_fma_mix_f32 v12, v9, v159, v12 op_sel:[0,1,0] op_sel_hi:[0,1,0]
	v_fma_mix_f32 v126, v6, v144, v180 op_sel_hi:[0,1,0]
	v_fma_mix_f32 v126, v7, v144, v126 op_sel:[0,1,0] op_sel_hi:[0,1,0]
	v_add_f32_dpp v12, v12, v12 row_ror:1 row_mask:0xf bank_mask:0xf bound_ctrl:1
	v_fma_mix_f32 v126, v8, v145, v126 op_sel_hi:[0,1,0]
	v_fma_mix_f32 v126, v9, v145, v126 op_sel:[0,1,0] op_sel_hi:[0,1,0]
	v_add_f32_dpp v12, v12, v12 row_ror:2 row_mask:0xf bank_mask:0xf bound_ctrl:1
	v_pk_fma_f32 v[48:49], v[166:167], v[70:71], v[6:7] op_sel:[0,1,0]
	v_pk_fma_f32 v[50:51], v[168:169], v[70:71], v[8:9] op_sel:[0,1,0]
	v_add_f32_dpp v12, v12, v12 row_ror:4 row_mask:0xf bank_mask:0xf bound_ctrl:1
	v_add_f32_dpp v105, v105, v105 row_ror:8 row_mask:0xf bank_mask:0xc
	v_add_f32_dpp v105, v81, v81 row_ror:8 row_mask:0xf bank_mask:0x3
	v_add_f32_dpp v12, v12, v12 row_ror:8 row_mask:0xf bank_mask:0xf bound_ctrl:1
	v_pk_fma_f32 v[6:7], v[162:163], v[12:13], v[48:49] op_sel_hi:[1,0,1] neg_lo:[1,0,0] neg_hi:[1,0,0]
	v_pk_fma_f32 v[8:9], v[164:165], v[12:13], v[50:51] op_sel_hi:[1,0,1] neg_lo:[1,0,0] neg_hi:[1,0,0]
	ds_read_b128 v[20:23], v10 offset:57600
	ds_read_b128 v[28:31], v10 offset:58112
	ds_read_b128 v[24:27], v10 offset:57856
	ds_read_b128 v[66:69], v11 offset:3584
	s_waitcnt lgkmcnt(4)
	v_fma_mix_f32 v12, v6, v188, v180 op_sel_hi:[0,1,0]
	v_fma_mix_f32 v12, v7, v188, v12 op_sel:[0,1,0] op_sel_hi:[0,1,0]
	v_fma_mix_f32 v12, v8, v189, v12 op_sel_hi:[0,1,0]
	v_fma_mix_f32 v12, v9, v189, v12 op_sel:[0,1,0] op_sel_hi:[0,1,0]
	v_fma_mix_f32 v127, v6, v160, v180 op_sel_hi:[0,1,0]
	v_fma_mix_f32 v127, v7, v160, v127 op_sel:[0,1,0] op_sel_hi:[0,1,0]
	v_add_f32_dpp v12, v12, v12 row_ror:1 row_mask:0xf bank_mask:0xf bound_ctrl:1
	v_fma_mix_f32 v127, v8, v161, v127 op_sel_hi:[0,1,0]
	v_fma_mix_f32 v127, v9, v161, v127 op_sel:[0,1,0] op_sel_hi:[0,1,0]
	v_add_f32_dpp v12, v12, v12 row_ror:2 row_mask:0xf bank_mask:0xf bound_ctrl:1
	v_pk_fma_f32 v[48:49], v[196:197], v[72:73], v[6:7] op_sel_hi:[1,0,1]
	v_pk_fma_f32 v[50:51], v[198:199], v[72:73], v[8:9] op_sel_hi:[1,0,1]
	v_add_f32_dpp v12, v12, v12 row_ror:4 row_mask:0xf bank_mask:0xf bound_ctrl:1
	v_add_f32_dpp v61, v61, v61 row_ror:8 row_mask:0xf bank_mask:0xc
	v_add_f32_dpp v61, v82, v82 row_ror:8 row_mask:0xf bank_mask:0x3
	v_add_f32_dpp v12, v12, v12 row_ror:8 row_mask:0xf bank_mask:0xf bound_ctrl:1
	v_pk_fma_f32 v[6:7], v[192:193], v[12:13], v[48:49] op_sel_hi:[1,0,1] neg_lo:[1,0,0] neg_hi:[1,0,0]
	v_pk_fma_f32 v[8:9], v[194:195], v[12:13], v[50:51] op_sel_hi:[1,0,1] neg_lo:[1,0,0] neg_hi:[1,0,0]
	ds_read_b128 v[36:39], v10 offset:58624
	ds_read_b128 v[44:47], v10 offset:59136
	ds_read_b128 v[40:43], v10 offset:58880
	v_fma_mix_f32 v12, v6, v204, v180 op_sel_hi:[0,1,0]
	v_fma_mix_f32 v12, v7, v204, v12 op_sel:[0,1,0] op_sel_hi:[0,1,0]
	v_fma_mix_f32 v12, v8, v205, v12 op_sel_hi:[0,1,0]
	v_fma_mix_f32 v12, v9, v205, v12 op_sel:[0,1,0] op_sel_hi:[0,1,0]
	v_fma_mix_f32 v128, v6, v190, v180 op_sel_hi:[0,1,0]
	v_fma_mix_f32 v128, v7, v190, v128 op_sel:[0,1,0] op_sel_hi:[0,1,0]
	v_add_f32_dpp v12, v12, v12 row_ror:1 row_mask:0xf bank_mask:0xf bound_ctrl:1
	v_fma_mix_f32 v128, v8, v191, v128 op_sel_hi:[0,1,0]
	v_fma_mix_f32 v128, v9, v191, v128 op_sel:[0,1,0] op_sel_hi:[0,1,0]
	v_add_f32_dpp v12, v12, v12 row_ror:2 row_mask:0xf bank_mask:0xf bound_ctrl:1
	v_pk_fma_f32 v[48:49], v[212:213], v[72:73], v[6:7] op_sel:[0,1,0]
	v_pk_fma_f32 v[50:51], v[214:215], v[72:73], v[8:9] op_sel:[0,1,0]
	v_add_f32_dpp v12, v12, v12 row_ror:4 row_mask:0xf bank_mask:0xf bound_ctrl:1
	v_add_f32_dpp v103, v103, v103 row_ror:4 row_mask:0xf bank_mask:0xa
	v_add_f32_dpp v103, v83, v83 row_ror:12 row_mask:0xf bank_mask:0x5
	v_add_f32_dpp v104, v104, v104 row_ror:4 row_mask:0xf bank_mask:0xa
	v_add_f32_dpp v12, v12, v12 row_ror:8 row_mask:0xf bank_mask:0xf bound_ctrl:1
	v_pk_fma_f32 v[6:7], v[208:209], v[12:13], v[48:49] op_sel_hi:[1,0,1] neg_lo:[1,0,0] neg_hi:[1,0,0]
	v_pk_fma_f32 v[8:9], v[210:211], v[12:13], v[50:51] op_sel_hi:[1,0,1] neg_lo:[1,0,0] neg_hi:[1,0,0]
	v_pk_mul_f32 v[6:7], v[6:7], v[200:201]
	v_pk_mul_f32 v[8:9], v[8:9], v[202:203]
	ds_read_b128 v[88:91], v10 offset:59648
	ds_read_b128 v[96:99], v10 offset:60160
	ds_read_b128 v[92:95], v10 offset:59904
	s_waitcnt lgkmcnt(3)
	v_fma_mix_f32 v12, v6, v20, v180 op_sel_hi:[0,1,0]
	v_fma_mix_f32 v12, v7, v20, v12 op_sel:[0,1,0] op_sel_hi:[0,1,0]
	v_fma_mix_f32 v12, v8, v21, v12 op_sel_hi:[0,1,0]
	v_fma_mix_f32 v12, v9, v21, v12 op_sel:[0,1,0] op_sel_hi:[0,1,0]
	v_fma_mix_f32 v129, v6, v206, v180 op_sel_hi:[0,1,0]
	v_fma_mix_f32 v129, v7, v206, v129 op_sel:[0,1,0] op_sel_hi:[0,1,0]
	v_add_f32_dpp v12, v12, v12 row_ror:1 row_mask:0xf bank_mask:0xf bound_ctrl:1
	v_fma_mix_f32 v129, v8, v207, v129 op_sel_hi:[0,1,0]
	v_fma_mix_f32 v129, v9, v207, v129 op_sel:[0,1,0] op_sel_hi:[0,1,0]
	v_add_f32_dpp v12, v12, v12 row_ror:2 row_mask:0xf bank_mask:0xf bound_ctrl:1
	v_pk_fma_f32 v[48:49], v[28:29], v[66:67], v[6:7] op_sel_hi:[1,0,1]
	v_pk_fma_f32 v[50:51], v[30:31], v[66:67], v[8:9] op_sel_hi:[1,0,1]
	v_add_f32_dpp v12, v12, v12 row_ror:4 row_mask:0xf bank_mask:0xf bound_ctrl:1
	v_add_f32_dpp v104, v100, v100 row_ror:12 row_mask:0xf bank_mask:0x5
	v_add_f32_dpp v105, v105, v105 row_ror:4 row_mask:0xf bank_mask:0xa
	v_add_f32_dpp v105, v101, v101 row_ror:12 row_mask:0xf bank_mask:0x5
	v_add_f32_dpp v12, v12, v12 row_ror:8 row_mask:0xf bank_mask:0xf bound_ctrl:1
	v_pk_fma_f32 v[6:7], v[24:25], v[12:13], v[48:49] op_sel_hi:[1,0,1] neg_lo:[1,0,0] neg_hi:[1,0,0]
	v_pk_fma_f32 v[8:9], v[26:27], v[12:13], v[50:51] op_sel_hi:[1,0,1] neg_lo:[1,0,0] neg_hi:[1,0,0]
	ds_read_b128 v[110:113], v10 offset:60672
	ds_read_b128 v[106:109], v10 offset:60416
	ds_read_b128 v[118:121], v10 offset:61184
	ds_read_b128 v[114:117], v10 offset:60928
	v_fma_mix_f32 v12, v6, v36, v180 op_sel_hi:[0,1,0]
	v_fma_mix_f32 v12, v7, v36, v12 op_sel:[0,1,0] op_sel_hi:[0,1,0]
	v_fma_mix_f32 v12, v8, v37, v12 op_sel_hi:[0,1,0]
	v_fma_mix_f32 v12, v9, v37, v12 op_sel:[0,1,0] op_sel_hi:[0,1,0]
	v_fma_mix_f32 v130, v6, v22, v180 op_sel_hi:[0,1,0]
	v_fma_mix_f32 v130, v7, v22, v130 op_sel:[0,1,0] op_sel_hi:[0,1,0]
	v_add_f32_dpp v12, v12, v12 row_ror:1 row_mask:0xf bank_mask:0xf bound_ctrl:1
	v_fma_mix_f32 v130, v8, v23, v130 op_sel_hi:[0,1,0]
	v_fma_mix_f32 v130, v9, v23, v130 op_sel:[0,1,0] op_sel_hi:[0,1,0]
	v_add_f32_dpp v12, v12, v12 row_ror:2 row_mask:0xf bank_mask:0xf bound_ctrl:1
	v_pk_fma_f32 v[48:49], v[44:45], v[66:67], v[6:7] op_sel:[0,1,0]
	v_pk_fma_f32 v[50:51], v[46:47], v[66:67], v[8:9] op_sel:[0,1,0]
	v_add_f32_dpp v12, v12, v12 row_ror:4 row_mask:0xf bank_mask:0xf bound_ctrl:1
	v_add_f32_dpp v61, v61, v61 row_ror:4 row_mask:0xf bank_mask:0xa
	v_add_f32_dpp v61, v102, v102 row_ror:12 row_mask:0xf bank_mask:0x5
	v_add_f32_dpp v12, v12, v12 row_ror:8 row_mask:0xf bank_mask:0xf bound_ctrl:1
	v_pk_fma_f32 v[6:7], v[40:41], v[12:13], v[48:49] op_sel_hi:[1,0,1] neg_lo:[1,0,0] neg_hi:[1,0,0]
	v_pk_fma_f32 v[8:9], v[42:43], v[12:13], v[50:51] op_sel_hi:[1,0,1] neg_lo:[1,0,0] neg_hi:[1,0,0]
	ds_read_b128 v[142:145], v10 offset:61696
	ds_read_b128 v[150:153], v10 offset:62208
	ds_read_b128 v[146:149], v10 offset:61952
	ds_read_b128 v[70:73], v11 offset:3840
	s_waitcnt lgkmcnt(4)
	v_fma_mix_f32 v12, v6, v88, v180 op_sel_hi:[0,1,0]
	v_fma_mix_f32 v12, v7, v88, v12 op_sel:[0,1,0] op_sel_hi:[0,1,0]
	v_fma_mix_f32 v12, v8, v89, v12 op_sel_hi:[0,1,0]
	v_fma_mix_f32 v12, v9, v89, v12 op_sel:[0,1,0] op_sel_hi:[0,1,0]
	v_fma_mix_f32 v131, v6, v38, v180 op_sel_hi:[0,1,0]
	v_fma_mix_f32 v131, v7, v38, v131 op_sel:[0,1,0] op_sel_hi:[0,1,0]
	v_add_f32_dpp v12, v12, v12 row_ror:1 row_mask:0xf bank_mask:0xf bound_ctrl:1
	v_fma_mix_f32 v131, v8, v39, v131 op_sel_hi:[0,1,0]
	v_fma_mix_f32 v131, v9, v39, v131 op_sel:[0,1,0] op_sel_hi:[0,1,0]
	v_add_f32_dpp v12, v12, v12 row_ror:2 row_mask:0xf bank_mask:0xf bound_ctrl:1
	v_pk_fma_f32 v[48:49], v[96:97], v[68:69], v[6:7] op_sel_hi:[1,0,1]
	v_pk_fma_f32 v[50:51], v[98:99], v[68:69], v[8:9] op_sel_hi:[1,0,1]
	v_add_f32_dpp v12, v12, v12 row_ror:4 row_mask:0xf bank_mask:0xf bound_ctrl:1
	v_cndmask_b32_e64 v62, v105, v103, s[38:39]
	v_cndmask_b32_e64 v63, v103, v105, s[38:39]
	v_add_f32_dpp v12, v12, v12 row_ror:8 row_mask:0xf bank_mask:0xf bound_ctrl:1
	v_pk_fma_f32 v[6:7], v[92:93], v[12:13], v[48:49] op_sel_hi:[1,0,1] neg_lo:[1,0,0] neg_hi:[1,0,0]
	v_pk_fma_f32 v[8:9], v[94:95], v[12:13], v[50:51] op_sel_hi:[1,0,1] neg_lo:[1,0,0] neg_hi:[1,0,0]
	ds_read_b128 v[158:161], v10 offset:62720
	ds_read_b128 v[166:169], v10 offset:63232
	ds_read_b128 v[162:165], v10 offset:62976
	v_fma_mix_f32 v12, v6, v110, v180 op_sel_hi:[0,1,0]
	v_fma_mix_f32 v12, v7, v110, v12 op_sel:[0,1,0] op_sel_hi:[0,1,0]
	v_fma_mix_f32 v12, v8, v111, v12 op_sel_hi:[0,1,0]
	v_fma_mix_f32 v12, v9, v111, v12 op_sel:[0,1,0] op_sel_hi:[0,1,0]
	v_fma_mix_f32 v132, v6, v90, v180 op_sel_hi:[0,1,0]
	v_fma_mix_f32 v132, v7, v90, v132 op_sel:[0,1,0] op_sel_hi:[0,1,0]
	v_add_f32_dpp v12, v12, v12 row_ror:1 row_mask:0xf bank_mask:0xf bound_ctrl:1
	v_fma_mix_f32 v132, v8, v91, v132 op_sel_hi:[0,1,0]
	v_fma_mix_f32 v132, v9, v91, v132 op_sel:[0,1,0] op_sel_hi:[0,1,0]
	v_add_f32_dpp v12, v12, v12 row_ror:2 row_mask:0xf bank_mask:0xf bound_ctrl:1
	v_pk_fma_f32 v[48:49], v[118:119], v[68:69], v[6:7] op_sel:[0,1,0]
	v_pk_fma_f32 v[50:51], v[120:121], v[68:69], v[8:9] op_sel:[0,1,0]
	v_add_f32_dpp v12, v12, v12 row_ror:4 row_mask:0xf bank_mask:0xf bound_ctrl:1
	v_cndmask_b32_e64 v64, v61, v104, s[38:39]
	v_cndmask_b32_e64 v65, v104, v61, s[38:39]
	v_add_f32_dpp v12, v12, v12 row_ror:8 row_mask:0xf bank_mask:0xf bound_ctrl:1
	v_pk_fma_f32 v[6:7], v[114:115], v[12:13], v[48:49] op_sel_hi:[1,0,1] neg_lo:[1,0,0] neg_hi:[1,0,0]
	v_pk_fma_f32 v[8:9], v[116:117], v[12:13], v[50:51] op_sel_hi:[1,0,1] neg_lo:[1,0,0] neg_hi:[1,0,0]
	v_pk_mul_f32 v[6:7], v[6:7], v[106:107]
	v_pk_mul_f32 v[8:9], v[8:9], v[108:109]
	ds_read_b128 v[188:191], v10 offset:63744
	ds_read_b128 v[196:199], v10 offset:64256
	ds_read_b128 v[192:195], v10 offset:64000
	s_waitcnt lgkmcnt(3)
	v_fma_mix_f32 v12, v6, v142, v180 op_sel_hi:[0,1,0]
	v_fma_mix_f32 v12, v7, v142, v12 op_sel:[0,1,0] op_sel_hi:[0,1,0]
	v_fma_mix_f32 v12, v8, v143, v12 op_sel_hi:[0,1,0]
	v_fma_mix_f32 v12, v9, v143, v12 op_sel:[0,1,0] op_sel_hi:[0,1,0]
	v_fma_mix_f32 v133, v6, v112, v180 op_sel_hi:[0,1,0]
	v_fma_mix_f32 v133, v7, v112, v133 op_sel:[0,1,0] op_sel_hi:[0,1,0]
	v_add_f32_dpp v12, v12, v12 row_ror:1 row_mask:0xf bank_mask:0xf bound_ctrl:1
	v_fma_mix_f32 v133, v8, v113, v133 op_sel_hi:[0,1,0]
	v_fma_mix_f32 v133, v9, v113, v133 op_sel:[0,1,0] op_sel_hi:[0,1,0]
	v_add_f32_dpp v12, v12, v12 row_ror:2 row_mask:0xf bank_mask:0xf bound_ctrl:1
	v_pk_fma_f32 v[48:49], v[150:151], v[70:71], v[6:7] op_sel_hi:[1,0,1]
	v_pk_fma_f32 v[50:51], v[152:153], v[70:71], v[8:9] op_sel_hi:[1,0,1]
	v_add_f32_dpp v12, v12, v12 row_ror:4 row_mask:0xf bank_mask:0xf bound_ctrl:1
	v_add_f32_dpp v62, v63, v62 quad_perm:[2,3,0,1] row_mask:0xf bank_mask:0xf bound_ctrl:1
	v_add_f32_dpp v63, v65, v64 quad_perm:[2,3,0,1] row_mask:0xf bank_mask:0xf bound_ctrl:1
	v_add_f32_dpp v12, v12, v12 row_ror:8 row_mask:0xf bank_mask:0xf bound_ctrl:1
	v_pk_fma_f32 v[6:7], v[146:147], v[12:13], v[48:49] op_sel_hi:[1,0,1] neg_lo:[1,0,0] neg_hi:[1,0,0]
	v_pk_fma_f32 v[8:9], v[148:149], v[12:13], v[50:51] op_sel_hi:[1,0,1] neg_lo:[1,0,0] neg_hi:[1,0,0]
	ds_read_b128 v[204:207], v10 offset:64768
	ds_read_b128 v[200:203], v10 offset:64512
	ds_read_b128 v[212:215], v10 offset:65280
	ds_read_b128 v[208:211], v10 offset:65024
	v_fma_mix_f32 v12, v6, v158, v180 op_sel_hi:[0,1,0]
	v_fma_mix_f32 v12, v7, v158, v12 op_sel:[0,1,0] op_sel_hi:[0,1,0]
	v_fma_mix_f32 v12, v8, v159, v12 op_sel_hi:[0,1,0]
	v_fma_mix_f32 v12, v9, v159, v12 op_sel:[0,1,0] op_sel_hi:[0,1,0]
	v_fma_mix_f32 v134, v6, v144, v180 op_sel_hi:[0,1,0]
	v_fma_mix_f32 v134, v7, v144, v134 op_sel:[0,1,0] op_sel_hi:[0,1,0]
	v_add_f32_dpp v12, v12, v12 row_ror:1 row_mask:0xf bank_mask:0xf bound_ctrl:1
	v_fma_mix_f32 v134, v8, v145, v134 op_sel_hi:[0,1,0]
	v_fma_mix_f32 v134, v9, v145, v134 op_sel:[0,1,0] op_sel_hi:[0,1,0]
	v_add_f32_dpp v12, v12, v12 row_ror:2 row_mask:0xf bank_mask:0xf bound_ctrl:1
	v_pk_fma_f32 v[48:49], v[166:167], v[70:71], v[6:7] op_sel:[0,1,0]
	v_pk_fma_f32 v[50:51], v[168:169], v[70:71], v[8:9] op_sel:[0,1,0]
	v_add_f32_dpp v12, v12, v12 row_ror:4 row_mask:0xf bank_mask:0xf bound_ctrl:1
	v_cndmask_b32_e64 v65, v63, v62, s[40:41]
	v_cndmask_b32_e64 v62, v62, v63, s[40:41]
	v_add_f32_dpp v12, v12, v12 row_ror:8 row_mask:0xf bank_mask:0xf bound_ctrl:1
	v_pk_fma_f32 v[6:7], v[162:163], v[12:13], v[48:49] op_sel_hi:[1,0,1] neg_lo:[1,0,0] neg_hi:[1,0,0]
	v_pk_fma_f32 v[8:9], v[164:165], v[12:13], v[50:51] op_sel_hi:[1,0,1] neg_lo:[1,0,0] neg_hi:[1,0,0]
	s_waitcnt lgkmcnt(0)
	v_fma_mix_f32 v12, v6, v188, v180 op_sel_hi:[0,1,0]
	v_fma_mix_f32 v12, v7, v188, v12 op_sel:[0,1,0] op_sel_hi:[0,1,0]
	v_fma_mix_f32 v12, v8, v189, v12 op_sel_hi:[0,1,0]
	v_fma_mix_f32 v12, v9, v189, v12 op_sel:[0,1,0] op_sel_hi:[0,1,0]
	v_fma_mix_f32 v135, v6, v160, v180 op_sel_hi:[0,1,0]
	v_fma_mix_f32 v135, v7, v160, v135 op_sel:[0,1,0] op_sel_hi:[0,1,0]
	v_add_f32_dpp v12, v12, v12 row_ror:1 row_mask:0xf bank_mask:0xf bound_ctrl:1
	v_fma_mix_f32 v135, v8, v161, v135 op_sel_hi:[0,1,0]
	v_fma_mix_f32 v135, v9, v161, v135 op_sel:[0,1,0] op_sel_hi:[0,1,0]
	v_add_f32_dpp v12, v12, v12 row_ror:2 row_mask:0xf bank_mask:0xf bound_ctrl:1
	v_pk_fma_f32 v[48:49], v[196:197], v[72:73], v[6:7] op_sel_hi:[1,0,1]
	v_pk_fma_f32 v[50:51], v[198:199], v[72:73], v[8:9] op_sel_hi:[1,0,1]
	v_add_f32_dpp v12, v12, v12 row_ror:4 row_mask:0xf bank_mask:0xf bound_ctrl:1
	v_add_f32_dpp v62, v62, v65 quad_perm:[1,0,3,2] row_mask:0xf bank_mask:0xf bound_ctrl:1
	v_cvt_pk_bf16_f32 v62, v62, v62
	v_add_f32_dpp v12, v12, v12 row_ror:8 row_mask:0xf bank_mask:0xf bound_ctrl:1
	v_pk_fma_f32 v[6:7], v[192:193], v[12:13], v[48:49] op_sel_hi:[1,0,1] neg_lo:[1,0,0] neg_hi:[1,0,0]
	v_pk_fma_f32 v[8:9], v[194:195], v[12:13], v[50:51] op_sel_hi:[1,0,1] neg_lo:[1,0,0] neg_hi:[1,0,0]
	s_waitcnt lgkmcnt(0)
	s_barrier
	v_xor_b32_e32 v10, 0x10000, v10
	v_xor_b32_e32 v11, 0x1000, v11
	ds_read_b128 v[66:69], v11 offset:0
	ds_read_b128 v[20:23], v10 offset:256
	ds_read_b128 v[28:31], v10 offset:768
	ds_read_b128 v[24:27], v10 offset:512
	ds_read_b128 v[36:39], v10 offset:1280
	ds_read_b128 v[44:47], v10 offset:1792
	ds_read_b128 v[40:43], v10 offset:1536
	ds_read_b128 v[88:91], v10 offset:2304
	ds_read_b128 v[96:99], v10 offset:2816
	ds_read_b128 v[92:95], v10 offset:2560
	v_fma_mix_f32 v12, v6, v204, v180 op_sel_hi:[0,1,0]
	v_fma_mix_f32 v12, v7, v204, v12 op_sel:[0,1,0] op_sel_hi:[0,1,0]
	v_fma_mix_f32 v12, v8, v205, v12 op_sel_hi:[0,1,0]
	v_fma_mix_f32 v12, v9, v205, v12 op_sel:[0,1,0] op_sel_hi:[0,1,0]
	v_fma_mix_f32 v136, v6, v190, v180 op_sel_hi:[0,1,0]
	v_fma_mix_f32 v136, v7, v190, v136 op_sel:[0,1,0] op_sel_hi:[0,1,0]
	v_add_f32_dpp v12, v12, v12 row_ror:1 row_mask:0xf bank_mask:0xf bound_ctrl:1
	v_fma_mix_f32 v136, v8, v191, v136 op_sel_hi:[0,1,0]
	v_fma_mix_f32 v136, v9, v191, v136 op_sel:[0,1,0] op_sel_hi:[0,1,0]
	v_add_f32_dpp v12, v12, v12 row_ror:2 row_mask:0xf bank_mask:0xf bound_ctrl:1
	v_pk_fma_f32 v[48:49], v[212:213], v[72:73], v[6:7] op_sel:[0,1,0]
	v_pk_fma_f32 v[50:51], v[214:215], v[72:73], v[8:9] op_sel:[0,1,0]
	v_add_f32_dpp v12, v12, v12 row_ror:4 row_mask:0xf bank_mask:0xf bound_ctrl:1
	global_store_short v[2:3], v62, off
	v_lshl_add_u64 v[2:3], v[2:3], 0, s[84:85]
	v_add_f32_dpp v12, v12, v12 row_ror:8 row_mask:0xf bank_mask:0xf bound_ctrl:1
	v_pk_fma_f32 v[6:7], v[208:209], v[12:13], v[48:49] op_sel_hi:[1,0,1] neg_lo:[1,0,0] neg_hi:[1,0,0]
	v_pk_fma_f32 v[8:9], v[210:211], v[12:13], v[50:51] op_sel_hi:[1,0,1] neg_lo:[1,0,0] neg_hi:[1,0,0]
	v_pk_mul_f32 v[6:7], v[6:7], v[200:201]
	v_pk_mul_f32 v[8:9], v[8:9], v[202:203]
	v_fma_mix_f32 v137, v6, v206, v180 op_sel_hi:[0,1,0]
	v_fma_mix_f32 v137, v7, v206, v137 op_sel:[0,1,0] op_sel_hi:[0,1,0]
	v_fma_mix_f32 v137, v8, v207, v137 op_sel_hi:[0,1,0]
	v_fma_mix_f32 v137, v9, v207, v137 op_sel:[0,1,0] op_sel_hi:[0,1,0]
	v_mov_b32_e32 v170, v2
	v_mov_b32_e32 v171, v3
	s_mov_b64 s[100:101], -1
	s_cmp_lg_u32 s28, 0x800000
	s_cbranch_scc1 .Lscan_cons_chunk
	v_add_f32_dpp v130, v130, v130 row_ror:8 row_mask:0xf bank_mask:0xc
	v_add_f32_dpp v130, v122, v122 row_ror:8 row_mask:0xf bank_mask:0x3
	v_add_f32_dpp v131, v131, v131 row_ror:8 row_mask:0xf bank_mask:0xc
	v_add_f32_dpp v131, v123, v123 row_ror:8 row_mask:0xf bank_mask:0x3
	v_add_f32_dpp v132, v132, v132 row_ror:8 row_mask:0xf bank_mask:0xc
	v_add_f32_dpp v132, v124, v124 row_ror:8 row_mask:0xf bank_mask:0x3
	v_add_f32_dpp v133, v133, v133 row_ror:8 row_mask:0xf bank_mask:0xc
	v_add_f32_dpp v133, v125, v125 row_ror:8 row_mask:0xf bank_mask:0x3
	v_add_f32_dpp v134, v134, v134 row_ror:8 row_mask:0xf bank_mask:0xc
	v_add_f32_dpp v134, v126, v126 row_ror:8 row_mask:0xf bank_mask:0x3
	v_add_f32_dpp v135, v135, v135 row_ror:8 row_mask:0xf bank_mask:0xc
	v_add_f32_dpp v135, v127, v127 row_ror:8 row_mask:0xf bank_mask:0x3
	v_add_f32_dpp v136, v136, v136 row_ror:8 row_mask:0xf bank_mask:0xc
	v_add_f32_dpp v136, v128, v128 row_ror:8 row_mask:0xf bank_mask:0x3
	v_add_f32_dpp v137, v137, v137 row_ror:8 row_mask:0xf bank_mask:0xc
	v_add_f32_dpp v137, v129, v129 row_ror:8 row_mask:0xf bank_mask:0x3
	v_add_f32_dpp v134, v134, v134 row_ror:4 row_mask:0xf bank_mask:0xa
	v_add_f32_dpp v134, v130, v130 row_ror:12 row_mask:0xf bank_mask:0x5
	v_add_f32_dpp v135, v135, v135 row_ror:4 row_mask:0xf bank_mask:0xa
	v_add_f32_dpp v135, v131, v131 row_ror:12 row_mask:0xf bank_mask:0x5
	v_add_f32_dpp v136, v136, v136 row_ror:4 row_mask:0xf bank_mask:0xa
	v_add_f32_dpp v136, v132, v132 row_ror:12 row_mask:0xf bank_mask:0x5
	v_add_f32_dpp v137, v137, v137 row_ror:4 row_mask:0xf bank_mask:0xa
	v_add_f32_dpp v137, v133, v133 row_ror:12 row_mask:0xf bank_mask:0x5
	v_cndmask_b32_e64 v62, v136, v134, s[38:39]
	v_cndmask_b32_e64 v63, v134, v136, s[38:39]
	v_cndmask_b32_e64 v64, v137, v135, s[38:39]
	v_cndmask_b32_e64 v65, v135, v137, s[38:39]
	v_add_f32_dpp v62, v63, v62 quad_perm:[2,3,0,1] row_mask:0xf bank_mask:0xf bound_ctrl:1
	s_nop 0
	v_add_f32_dpp v63, v65, v64 quad_perm:[2,3,0,1] row_mask:0xf bank_mask:0xf bound_ctrl:1
	v_cndmask_b32_e64 v65, v63, v62, s[40:41]
	v_cndmask_b32_e64 v62, v62, v63, s[40:41]
	s_nop 1
	v_add_f32_dpp v62, v62, v65 quad_perm:[1,0,3,2] row_mask:0xf bank_mask:0xf bound_ctrl:1
	v_cvt_pk_bf16_f32 v62, v62, v62
	global_store_short v[2:3], v62, off
	s_branch .LBB0_53
